# non-temporal policy on read-once streaming loads: f32 weights in the prologue transposes, adaLN weights, pre-norm x rows, ctx split-K partials
# speedup vs baseline: 1.0356x; 1.0300x over previous
; __device__ __forceinline__ void prologue(const Params& p, LAS unsigned char* lds) {
;     ...
;         for (int item = blockIdx.x; item < 576; item += G) {
;             const int l = item / 288, n0 = (item % 288) * 32;
;             const float* wp = p.in[I_ADAW] + (size_t)l * 1024 * 9216 + n0 + 4 * cl;
;             f32x4 acc[5];
; #pragma unroll
;             for (int b = 0; b < 5; ++b) acc[b] = (f32x4){0.f, 0.f, 0.f, 0.f};
; #pragma unroll
;             for (int s = 0; s < 16; ++s) { const int k = kr + 64 * s; const f32x4 w4 = *(const f32x4*)(wp + (size_t)k * 9216);
; #pragma unroll
;                 for (int b = 0; b < 5; ++b) acc[b] += w4 * sil[b * 1024 + k]; }
.LBB0_24:
	s_mul_hi_i32 s2, s12, 0x38e38e39
	s_lshr_b32 s3, s2, 31
	s_ashr_i32 s13, s2, 6
	s_add_i32 s13, s13, s3
	s_mul_i32 s2, s13, 0xffffdc00
	s_add_i32 s2, s9, s2
	s_mul_i32 s4, s13, 0x2400000
	s_mul_hi_i32 s3, s13, 0x2400000
	s_add_u32 s14, s24, s4
	s_addc_u32 s15, s25, s3
	s_ashr_i32 s3, s2, 31
	s_lshl_b64 s[4:5], s[2:3], 2
	s_add_u32 s4, s14, s4
	s_addc_u32 s5, s15, s5
	v_lshl_add_u64 v[48:49], s[4:5], 0, v[20:21]
	v_lshl_add_u64 v[0:1], v[48:49], 0, v[22:23]
	v_add_co_u32_e64 v2, s[4:5], s6, v0
	global_load_dwordx4 v[12:15], v[0:1], off nt
	s_nop 0
	v_addc_co_u32_e64 v3, s[4:5], 0, v1, s[4:5]
	global_load_dwordx4 v[60:63], v[2:3], off nt
	v_add_co_u32_e64 v2, s[4:5], s7, v0
	s_nop 1
	v_addc_co_u32_e64 v3, s[4:5], 0, v1, s[4:5]
	v_add_co_u32_e64 v0, s[4:5], s8, v0
	global_load_dwordx4 v[64:67], v[2:3], off nt
	s_nop 0
	v_addc_co_u32_e64 v1, s[4:5], 0, v1, s[4:5]
	global_load_dwordx4 v[68:71], v[0:1], off nt
	v_lshl_add_u64 v[0:1], v[48:49], 0, v[24:25]
	global_load_dwordx4 v[78:81], v[0:1], off nt
	v_lshl_add_u64 v[0:1], v[48:49], 0, v[26:27]
	ds_read2st64_b32 v[86:87], v74 offset1:1
	ds_read2st64_b32 v[88:89], v74 offset0:2 offset1:3
	ds_read2st64_b32 v[90:91], v74 offset0:4 offset1:5
	ds_read2st64_b32 v[52:53], v74 offset0:6 offset1:7
	ds_read2st64_b32 v[92:93], v74 offset0:16 offset1:17
	ds_read2st64_b32 v[94:95], v74 offset0:18 offset1:19
	ds_read2st64_b32 v[96:97], v74 offset0:20 offset1:21
	ds_read2st64_b32 v[54:55], v74 offset0:22 offset1:23
	global_load_dwordx4 v[82:85], v[0:1], off nt
	v_lshl_add_u64 v[0:1], v[48:49], 0, v[28:29]
	ds_read2st64_b32 v[98:99], v74 offset0:32 offset1:33
	ds_read2st64_b32 v[100:101], v74 offset0:34 offset1:35
	ds_read2st64_b32 v[102:103], v74 offset0:36 offset1:37
	ds_read2st64_b32 v[56:57], v74 offset0:38 offset1:39
	ds_read2st64_b32 v[104:105], v74 offset0:48 offset1:49
	ds_read2st64_b32 v[106:107], v74 offset0:50 offset1:51
	ds_read2st64_b32 v[108:109], v74 offset0:52 offset1:53
	ds_read2st64_b32 v[58:59], v74 offset0:54 offset1:55
	ds_read2st64_b32 v[110:111], v74 offset0:64 offset1:65
	ds_read2st64_b32 v[112:113], v74 offset0:66 offset1:67
	ds_read2st64_b32 v[114:115], v74 offset0:68 offset1:69
	ds_read2st64_b32 v[50:51], v74 offset0:70 offset1:71
	global_load_dwordx4 v[8:11], v[0:1], off nt
	v_lshl_add_u64 v[0:1], v[48:49], 0, v[30:31]
	v_lshl_add_u64 v[2:3], v[48:49], 0, v[32:33]
	global_load_dwordx4 v[4:7], v[0:1], off nt
	s_nop 0
	global_load_dwordx4 v[0:3], v[2:3], off nt
	s_waitcnt lgkmcnt(14)
	v_mov_b32_e32 v18, v87
	v_mov_b32_e32 v116, v93
	s_waitcnt lgkmcnt(11)
	v_mov_b32_e32 v118, v99
	s_waitcnt lgkmcnt(7)
	v_mov_b32_e32 v120, v105
	s_waitcnt lgkmcnt(3)
	v_mov_b32_e32 v122, v111
	s_waitcnt vmcnt(8)
	v_pk_fma_f32 v[124:125], v[14:15], v[86:87], 0 op_sel_hi:[1,0,0]
	v_pk_fma_f32 v[86:87], v[12:13], v[86:87], 0 op_sel_hi:[1,0,0]
	v_pk_fma_f32 v[126:127], v[14:15], v[92:93], 0 op_sel_hi:[1,0,0]
	v_pk_fma_f32 v[92:93], v[12:13], v[92:93], 0 op_sel_hi:[1,0,0]
	v_pk_fma_f32 v[128:129], v[14:15], v[98:99], 0 op_sel_hi:[1,0,0]
	v_pk_fma_f32 v[98:99], v[12:13], v[98:99], 0 op_sel_hi:[1,0,0]
	v_pk_fma_f32 v[130:131], v[14:15], v[104:105], 0 op_sel_hi:[1,0,0]
	v_pk_fma_f32 v[104:105], v[12:13], v[104:105], 0 op_sel_hi:[1,0,0]
	v_pk_fma_f32 v[14:15], v[14:15], v[110:111], 0 op_sel_hi:[1,0,0]
	v_pk_fma_f32 v[12:13], v[12:13], v[110:111], 0 op_sel_hi:[1,0,0]
	s_waitcnt vmcnt(7)
	v_pk_fma_f32 v[110:111], v[62:63], v[18:19], v[124:125] op_sel_hi:[1,0,1]
	v_pk_fma_f32 v[86:87], v[60:61], v[18:19], v[86:87] op_sel_hi:[1,0,1]
	v_pk_fma_f32 v[124:125], v[62:63], v[116:117], v[126:127] op_sel_hi:[1,0,1]
	v_pk_fma_f32 v[92:93], v[60:61], v[116:117], v[92:93] op_sel_hi:[1,0,1]
	v_pk_fma_f32 v[116:117], v[62:63], v[118:119], v[128:129] op_sel_hi:[1,0,1]
	v_pk_fma_f32 v[98:99], v[60:61], v[118:119], v[98:99] op_sel_hi:[1,0,1]
	v_pk_fma_f32 v[118:119], v[62:63], v[120:121], v[130:131] op_sel_hi:[1,0,1]
	v_pk_fma_f32 v[104:105], v[60:61], v[120:121], v[104:105] op_sel_hi:[1,0,1]
	v_pk_fma_f32 v[14:15], v[62:63], v[122:123], v[14:15] op_sel_hi:[1,0,1]
	v_pk_fma_f32 v[12:13], v[60:61], v[122:123], v[12:13] op_sel_hi:[1,0,1]
	s_waitcnt vmcnt(6)
	v_pk_fma_f32 v[60:61], v[66:67], v[88:89], v[110:111] op_sel_hi:[1,0,1]
	v_pk_fma_f32 v[62:63], v[64:65], v[88:89], v[86:87] op_sel_hi:[1,0,1]
	v_mov_b32_e32 v18, v89
	v_pk_fma_f32 v[86:87], v[66:67], v[94:95], v[124:125] op_sel_hi:[1,0,1]
	v_pk_fma_f32 v[92:93], v[64:65], v[94:95], v[92:93] op_sel_hi:[1,0,1]
	s_waitcnt vmcnt(5)
	v_pk_fma_f32 v[60:61], v[70:71], v[18:19], v[60:61] op_sel_hi:[1,0,1]
	v_pk_fma_f32 v[62:63], v[68:69], v[18:19], v[62:63] op_sel_hi:[1,0,1]
	v_mov_b32_e32 v18, v95
	v_pk_fma_f32 v[110:111], v[66:67], v[100:101], v[116:117] op_sel_hi:[1,0,1]
	v_pk_fma_f32 v[98:99], v[64:65], v[100:101], v[98:99] op_sel_hi:[1,0,1]
	v_pk_fma_f32 v[116:117], v[66:67], v[106:107], v[118:119] op_sel_hi:[1,0,1]
	v_pk_fma_f32 v[104:105], v[64:65], v[106:107], v[104:105] op_sel_hi:[1,0,1]
	s_waitcnt lgkmcnt(2)
	v_pk_fma_f32 v[14:15], v[66:67], v[112:113], v[14:15] op_sel_hi:[1,0,1]
	v_pk_fma_f32 v[12:13], v[64:65], v[112:113], v[12:13] op_sel_hi:[1,0,1]
	v_pk_fma_f32 v[64:65], v[70:71], v[18:19], v[86:87] op_sel_hi:[1,0,1]
	v_pk_fma_f32 v[66:67], v[68:69], v[18:19], v[92:93] op_sel_hi:[1,0,1]
	v_mov_b32_e32 v18, v101
	v_pk_fma_f32 v[86:87], v[70:71], v[18:19], v[110:111] op_sel_hi:[1,0,1]
	v_pk_fma_f32 v[88:89], v[68:69], v[18:19], v[98:99] op_sel_hi:[1,0,1]
	v_mov_b32_e32 v18, v107
	v_pk_fma_f32 v[92:93], v[70:71], v[18:19], v[116:117] op_sel_hi:[1,0,1]
	v_pk_fma_f32 v[94:95], v[68:69], v[18:19], v[104:105] op_sel_hi:[1,0,1]
	v_mov_b32_e32 v18, v113
	v_pk_fma_f32 v[12:13], v[68:69], v[18:19], v[12:13] op_sel_hi:[1,0,1]
	v_pk_fma_f32 v[14:15], v[70:71], v[18:19], v[14:15] op_sel_hi:[1,0,1]
	s_waitcnt vmcnt(4)
; __device__ __forceinline__ void prologue(const Params& p, LAS unsigned char* lds) {
;     ...
;             for (int s = 0; s < 16; ++s) { const int k = kr + 64 * s; const f32x4 w4 = *(const f32x4*)(wp + (size_t)k * 9216);
; #pragma unroll
;                 for (int b = 0; b < 5; ++b) acc[b] += w4 * sil[b * 1024 + k]; }
	v_pk_fma_f32 v[60:61], v[80:81], v[90:91], v[60:61] op_sel_hi:[1,0,1]
	v_pk_fma_f32 v[62:63], v[78:79], v[90:91], v[62:63] op_sel_hi:[1,0,1]
	v_pk_fma_f32 v[66:67], v[78:79], v[96:97], v[66:67] op_sel_hi:[1,0,1]
	v_pk_fma_f32 v[70:71], v[78:79], v[102:103], v[88:89] op_sel_hi:[1,0,1]
	v_pk_fma_f32 v[88:89], v[78:79], v[108:109], v[94:95] op_sel_hi:[1,0,1]
	s_waitcnt lgkmcnt(1)
	v_pk_fma_f32 v[78:79], v[78:79], v[114:115], v[12:13] op_sel_hi:[1,0,1]
	v_mov_b32_e32 v12, v91
	v_pk_fma_f32 v[64:65], v[80:81], v[96:97], v[64:65] op_sel_hi:[1,0,1]
	s_waitcnt vmcnt(3)
	v_pk_fma_f32 v[60:61], v[84:85], v[12:13], v[60:61] op_sel_hi:[1,0,1]
	v_pk_fma_f32 v[90:91], v[82:83], v[12:13], v[62:63] op_sel_hi:[1,0,1]
	v_mov_b32_e32 v18, v97
	v_lshl_add_u64 v[12:13], v[48:49], 0, v[34:35]
	v_pk_fma_f32 v[68:69], v[80:81], v[102:103], v[86:87] op_sel_hi:[1,0,1]
	v_pk_fma_f32 v[86:87], v[80:81], v[108:109], v[92:93] op_sel_hi:[1,0,1]
	v_pk_fma_f32 v[80:81], v[80:81], v[114:115], v[14:15] op_sel_hi:[1,0,1]
	global_load_dwordx4 v[12:15], v[12:13], off nt
	v_pk_fma_f32 v[64:65], v[84:85], v[18:19], v[64:65] op_sel_hi:[1,0,1]
	v_pk_fma_f32 v[66:67], v[82:83], v[18:19], v[66:67] op_sel_hi:[1,0,1]
	v_mov_b32_e32 v18, v103
	v_pk_fma_f32 v[68:69], v[84:85], v[18:19], v[68:69] op_sel_hi:[1,0,1]
	v_pk_fma_f32 v[70:71], v[82:83], v[18:19], v[70:71] op_sel_hi:[1,0,1]
	v_mov_b32_e32 v18, v109
	v_pk_fma_f32 v[86:87], v[84:85], v[18:19], v[86:87] op_sel_hi:[1,0,1]
	v_pk_fma_f32 v[88:89], v[82:83], v[18:19], v[88:89] op_sel_hi:[1,0,1]
	v_mov_b32_e32 v18, v115
	v_pk_fma_f32 v[80:81], v[84:85], v[18:19], v[80:81] op_sel_hi:[1,0,1]
	v_pk_fma_f32 v[78:79], v[82:83], v[18:19], v[78:79] op_sel_hi:[1,0,1]
	s_waitcnt vmcnt(3)
	v_pk_fma_f32 v[82:83], v[10:11], v[52:53], v[60:61] op_sel_hi:[1,0,1]
	v_lshl_add_u64 v[60:61], v[48:49], 0, v[36:37]
	v_pk_fma_f32 v[84:85], v[8:9], v[52:53], v[90:91] op_sel_hi:[1,0,1]
	v_mov_b32_e32 v18, v53
	global_load_dwordx4 v[60:63], v[60:61], off nt
	v_pk_fma_f32 v[64:65], v[10:11], v[54:55], v[64:65] op_sel_hi:[1,0,1]
	v_pk_fma_f32 v[66:67], v[8:9], v[54:55], v[66:67] op_sel_hi:[1,0,1]
	v_pk_fma_f32 v[70:71], v[8:9], v[56:57], v[70:71] op_sel_hi:[1,0,1]
	v_pk_fma_f32 v[88:89], v[8:9], v[58:59], v[88:89] op_sel_hi:[1,0,1]
	s_waitcnt lgkmcnt(0)
	v_pk_fma_f32 v[78:79], v[8:9], v[50:51], v[78:79] op_sel_hi:[1,0,1]
	v_lshl_add_u64 v[8:9], v[48:49], 0, v[38:39]
	s_waitcnt vmcnt(3)
	v_pk_fma_f32 v[82:83], v[6:7], v[18:19], v[82:83] op_sel_hi:[1,0,1]
	v_pk_fma_f32 v[84:85], v[4:5], v[18:19], v[84:85] op_sel_hi:[1,0,1]
	v_mov_b32_e32 v18, v55
	v_pk_fma_f32 v[68:69], v[10:11], v[56:57], v[68:69] op_sel_hi:[1,0,1]
	v_pk_fma_f32 v[86:87], v[10:11], v[58:59], v[86:87] op_sel_hi:[1,0,1]
	v_pk_fma_f32 v[80:81], v[10:11], v[50:51], v[80:81] op_sel_hi:[1,0,1]
	global_load_dwordx4 v[8:11], v[8:9], off nt
	v_pk_fma_f32 v[64:65], v[6:7], v[18:19], v[64:65] op_sel_hi:[1,0,1]
	v_pk_fma_f32 v[66:67], v[4:5], v[18:19], v[66:67] op_sel_hi:[1,0,1]
	v_mov_b32_e32 v18, v57
	v_pk_fma_f32 v[56:57], v[6:7], v[18:19], v[68:69] op_sel_hi:[1,0,1]
	v_pk_fma_f32 v[68:69], v[4:5], v[18:19], v[70:71] op_sel_hi:[1,0,1]
	v_mov_b32_e32 v18, v59
	v_pk_fma_f32 v[70:71], v[6:7], v[18:19], v[86:87] op_sel_hi:[1,0,1]
	v_pk_fma_f32 v[86:87], v[4:5], v[18:19], v[88:89] op_sel_hi:[1,0,1]
	v_mov_b32_e32 v18, v51
	v_lshl_add_u64 v[52:53], v[48:49], 0, v[40:41]
	v_pk_fma_f32 v[78:79], v[4:5], v[18:19], v[78:79] op_sel_hi:[1,0,1]
	v_lshl_add_u64 v[4:5], v[48:49], 0, v[42:43]
	global_load_dwordx4 v[52:55], v[52:53], off nt
	v_pk_fma_f32 v[80:81], v[6:7], v[18:19], v[80:81] op_sel_hi:[1,0,1]
	ds_read2st64_b32 v[88:89], v74 offset0:8 offset1:9
	ds_read2st64_b32 v[90:91], v74 offset0:10 offset1:11
	ds_read2st64_b32 v[92:93], v74 offset0:12 offset1:13
	ds_read2st64_b32 v[94:95], v74 offset0:14 offset1:15
	ds_read2st64_b32 v[96:97], v74 offset0:24 offset1:25
	global_load_dwordx4 v[4:7], v[4:5], off nt
	ds_read2st64_b32 v[98:99], v74 offset0:26 offset1:27
	ds_read2st64_b32 v[100:101], v74 offset0:28 offset1:29
	ds_read2st64_b32 v[102:103], v74 offset0:30 offset1:31
	ds_read2st64_b32 v[104:105], v74 offset0:40 offset1:41
	v_lshl_add_u64 v[50:51], v[48:49], 0, v[44:45]
	ds_read2st64_b32 v[106:107], v74 offset0:42 offset1:43
	ds_read2st64_b32 v[108:109], v74 offset0:44 offset1:45
	ds_read2st64_b32 v[110:111], v74 offset0:46 offset1:47
	v_lshl_add_u64 v[48:49], v[48:49], 0, v[46:47]
	ds_read2st64_b32 v[114:115], v74 offset0:56 offset1:57
	s_waitcnt vmcnt(5) lgkmcnt(4)
	v_pk_fma_f32 v[112:113], v[2:3], v[104:105], v[56:57] op_sel_hi:[1,0,1]
	global_load_dwordx4 v[56:59], v[50:51], off nt
	ds_read2st64_b32 v[116:117], v74 offset0:58 offset1:59
	ds_read2st64_b32 v[118:119], v74 offset0:60 offset1:61
	ds_read2st64_b32 v[120:121], v74 offset0:62 offset1:63
	global_load_dwordx4 v[48:51], v[48:49], off nt
	ds_read2st64_b32 v[122:123], v74 offset0:72 offset1:73
	v_pk_fma_f32 v[82:83], v[2:3], v[88:89], v[82:83] op_sel_hi:[1,0,1]
	v_pk_fma_f32 v[84:85], v[0:1], v[88:89], v[84:85] op_sel_hi:[1,0,1]
	v_mov_b32_e32 v18, v89
	v_pk_fma_f32 v[64:65], v[2:3], v[96:97], v[64:65] op_sel_hi:[1,0,1]
	v_pk_fma_f32 v[66:67], v[0:1], v[96:97], v[66:67] op_sel_hi:[1,0,1]
	v_pk_fma_f32 v[68:69], v[0:1], v[104:105], v[68:69] op_sel_hi:[1,0,1]
	s_waitcnt lgkmcnt(4)
	v_pk_fma_f32 v[70:71], v[2:3], v[114:115], v[70:71] op_sel_hi:[1,0,1]
	v_pk_fma_f32 v[86:87], v[0:1], v[114:115], v[86:87] op_sel_hi:[1,0,1]
	s_waitcnt lgkmcnt(0)
	v_pk_fma_f32 v[2:3], v[2:3], v[122:123], v[80:81] op_sel_hi:[1,0,1]
	v_pk_fma_f32 v[0:1], v[0:1], v[122:123], v[78:79] op_sel_hi:[1,0,1]
	ds_read2st64_b32 v[124:125], v74 offset0:74 offset1:75
	ds_read2st64_b32 v[126:127], v74 offset0:76 offset1:77
	ds_read2st64_b32 v[128:129], v74 offset0:78 offset1:79
	s_waitcnt vmcnt(6)
; __device__ __forceinline__ void prologue(const Params& p, LAS unsigned char* lds) {
;     ...
;             for (int s = 0; s < 16; ++s) { const int k = kr + 64 * s; const f32x4 w4 = *(const f32x4*)(wp + (size_t)k * 9216);
; #pragma unroll
;                 for (int b = 0; b < 5; ++b) acc[b] += w4 * sil[b * 1024 + k]; }
	v_pk_fma_f32 v[78:79], v[14:15], v[18:19], v[82:83] op_sel_hi:[1,0,1]
	v_pk_fma_f32 v[80:81], v[12:13], v[18:19], v[84:85] op_sel_hi:[1,0,1]
	v_mov_b32_e32 v18, v97
	v_pk_fma_f32 v[64:65], v[14:15], v[18:19], v[64:65] op_sel_hi:[1,0,1]
	v_pk_fma_f32 v[66:67], v[12:13], v[18:19], v[66:67] op_sel_hi:[1,0,1]
	v_mov_b32_e32 v18, v105
	v_pk_fma_f32 v[82:83], v[14:15], v[18:19], v[112:113] op_sel_hi:[1,0,1]
	v_pk_fma_f32 v[68:69], v[12:13], v[18:19], v[68:69] op_sel_hi:[1,0,1]
	v_mov_b32_e32 v18, v115
	v_pk_fma_f32 v[70:71], v[14:15], v[18:19], v[70:71] op_sel_hi:[1,0,1]
	v_pk_fma_f32 v[84:85], v[12:13], v[18:19], v[86:87] op_sel_hi:[1,0,1]
	v_mov_b32_e32 v18, v123
	v_pk_fma_f32 v[2:3], v[14:15], v[18:19], v[2:3] op_sel_hi:[1,0,1]
	v_pk_fma_f32 v[0:1], v[12:13], v[18:19], v[0:1] op_sel_hi:[1,0,1]
	v_mov_b32_e32 v18, v91
	s_waitcnt vmcnt(5)
	v_pk_fma_f32 v[12:13], v[62:63], v[90:91], v[78:79] op_sel_hi:[1,0,1]
	v_pk_fma_f32 v[14:15], v[60:61], v[90:91], v[80:81] op_sel_hi:[1,0,1]
	v_pk_fma_f32 v[64:65], v[62:63], v[98:99], v[64:65] op_sel_hi:[1,0,1]
	v_pk_fma_f32 v[66:67], v[60:61], v[98:99], v[66:67] op_sel_hi:[1,0,1]
	v_pk_fma_f32 v[78:79], v[62:63], v[106:107], v[82:83] op_sel_hi:[1,0,1]
	v_pk_fma_f32 v[68:69], v[60:61], v[106:107], v[68:69] op_sel_hi:[1,0,1]
	v_pk_fma_f32 v[70:71], v[62:63], v[116:117], v[70:71] op_sel_hi:[1,0,1]
	v_pk_fma_f32 v[80:81], v[60:61], v[116:117], v[84:85] op_sel_hi:[1,0,1]
	s_waitcnt lgkmcnt(2)
	v_pk_fma_f32 v[2:3], v[62:63], v[124:125], v[2:3] op_sel_hi:[1,0,1]
	v_pk_fma_f32 v[0:1], v[60:61], v[124:125], v[0:1] op_sel_hi:[1,0,1]
	s_waitcnt vmcnt(4)
	v_pk_fma_f32 v[12:13], v[10:11], v[18:19], v[12:13] op_sel_hi:[1,0,1]
	v_pk_fma_f32 v[14:15], v[8:9], v[18:19], v[14:15] op_sel_hi:[1,0,1]
	v_mov_b32_e32 v18, v99
	v_pk_fma_f32 v[60:61], v[10:11], v[18:19], v[64:65] op_sel_hi:[1,0,1]
	v_pk_fma_f32 v[62:63], v[8:9], v[18:19], v[66:67] op_sel_hi:[1,0,1]
	v_mov_b32_e32 v18, v107
	v_pk_fma_f32 v[64:65], v[10:11], v[18:19], v[78:79] op_sel_hi:[1,0,1]
	v_pk_fma_f32 v[66:67], v[8:9], v[18:19], v[68:69] op_sel_hi:[1,0,1]
	v_mov_b32_e32 v18, v117
	v_pk_fma_f32 v[68:69], v[10:11], v[18:19], v[70:71] op_sel_hi:[1,0,1]
	v_pk_fma_f32 v[70:71], v[8:9], v[18:19], v[80:81] op_sel_hi:[1,0,1]
	v_mov_b32_e32 v18, v125
	v_pk_fma_f32 v[2:3], v[10:11], v[18:19], v[2:3] op_sel_hi:[1,0,1]
	v_pk_fma_f32 v[0:1], v[8:9], v[18:19], v[0:1] op_sel_hi:[1,0,1]
	s_waitcnt vmcnt(3)
	v_pk_fma_f32 v[8:9], v[54:55], v[92:93], v[12:13] op_sel_hi:[1,0,1]
	v_pk_fma_f32 v[10:11], v[52:53], v[92:93], v[14:15] op_sel_hi:[1,0,1]
	v_mov_b32_e32 v18, v93
	v_pk_fma_f32 v[12:13], v[54:55], v[100:101], v[60:61] op_sel_hi:[1,0,1]
	v_pk_fma_f32 v[14:15], v[52:53], v[100:101], v[62:63] op_sel_hi:[1,0,1]
	s_waitcnt vmcnt(2)
	v_pk_fma_f32 v[8:9], v[6:7], v[18:19], v[8:9] op_sel_hi:[1,0,1]
	v_pk_fma_f32 v[10:11], v[4:5], v[18:19], v[10:11] op_sel_hi:[1,0,1]
	v_mov_b32_e32 v18, v101
	v_pk_fma_f32 v[60:61], v[54:55], v[108:109], v[64:65] op_sel_hi:[1,0,1]
	v_pk_fma_f32 v[62:63], v[52:53], v[108:109], v[66:67] op_sel_hi:[1,0,1]
	v_pk_fma_f32 v[12:13], v[6:7], v[18:19], v[12:13] op_sel_hi:[1,0,1]
	v_pk_fma_f32 v[14:15], v[4:5], v[18:19], v[14:15] op_sel_hi:[1,0,1]
	v_mov_b32_e32 v18, v109
	v_pk_fma_f32 v[64:65], v[54:55], v[118:119], v[68:69] op_sel_hi:[1,0,1]
	v_pk_fma_f32 v[66:67], v[52:53], v[118:119], v[70:71] op_sel_hi:[1,0,1]
	s_waitcnt lgkmcnt(1)
	v_pk_fma_f32 v[2:3], v[54:55], v[126:127], v[2:3] op_sel_hi:[1,0,1]
	v_pk_fma_f32 v[0:1], v[52:53], v[126:127], v[0:1] op_sel_hi:[1,0,1]
	v_pk_fma_f32 v[52:53], v[6:7], v[18:19], v[60:61] op_sel_hi:[1,0,1]
	v_pk_fma_f32 v[54:55], v[4:5], v[18:19], v[62:63] op_sel_hi:[1,0,1]
	v_mov_b32_e32 v18, v119
	v_pk_fma_f32 v[60:61], v[6:7], v[18:19], v[64:65] op_sel_hi:[1,0,1]
	v_pk_fma_f32 v[62:63], v[4:5], v[18:19], v[66:67] op_sel_hi:[1,0,1]
	v_mov_b32_e32 v18, v127
	v_pk_fma_f32 v[2:3], v[6:7], v[18:19], v[2:3] op_sel_hi:[1,0,1]
	v_pk_fma_f32 v[0:1], v[4:5], v[18:19], v[0:1] op_sel_hi:[1,0,1]
	s_waitcnt vmcnt(1)
	v_pk_fma_f32 v[6:7], v[56:57], v[94:95], v[10:11] op_sel_hi:[1,0,1]
	v_mov_b32_e32 v18, v95
	s_waitcnt vmcnt(0)
	v_pk_fma_f32 v[6:7], v[48:49], v[18:19], v[6:7] op_sel_hi:[1,0,1]
	v_pk_fma_f32 v[4:5], v[58:59], v[94:95], v[8:9] op_sel_hi:[1,0,1]
	v_pk_fma_f32 v[10:11], v[56:57], v[102:103], v[14:15] op_sel_hi:[1,0,1]
	v_pk_fma_f32 v[14:15], v[56:57], v[110:111], v[54:55] op_sel_hi:[1,0,1]
	v_pk_fma_f32 v[54:55], v[56:57], v[120:121], v[62:63] op_sel_hi:[1,0,1]
	s_waitcnt lgkmcnt(0)
; __device__ __forceinline__ void prologue(const Params& p, LAS unsigned char* lds) {
;     ...
;             for (int b = 0; b < 5; ++b)
; #pragma unroll
;                 for (int q = 0; q < 4; ++q) { float v = acc[b][q]; v += __shfl_xor(v, 8); v += __shfl_xor(v, 16); v += __shfl_xor(v, 32); acc[b][q] = v; }
;             if (lane < 8) {
; #pragma unroll
;                 for (int b = 0; b < 5; ++b)
; #pragma unroll
;                     for (int q = 0; q < 4; ++q) part[(wave * 5 + b) * 32 + 4 * lane + q] = acc[b][q];
;             }
	v_pk_fma_f32 v[0:1], v[56:57], v[128:129], v[0:1] op_sel_hi:[1,0,1]
	ds_bpermute_b32 v56, v17, v6
	ds_bpermute_b32 v57, v17, v7
	v_pk_fma_f32 v[8:9], v[58:59], v[102:103], v[12:13] op_sel_hi:[1,0,1]
	v_pk_fma_f32 v[4:5], v[50:51], v[18:19], v[4:5] op_sel_hi:[1,0,1]
	v_mov_b32_e32 v18, v103
	v_pk_fma_f32 v[12:13], v[58:59], v[110:111], v[52:53] op_sel_hi:[1,0,1]
	v_pk_fma_f32 v[8:9], v[50:51], v[18:19], v[8:9] op_sel_hi:[1,0,1]
	v_pk_fma_f32 v[10:11], v[48:49], v[18:19], v[10:11] op_sel_hi:[1,0,1]
	v_mov_b32_e32 v18, v111
	v_pk_fma_f32 v[52:53], v[58:59], v[120:121], v[60:61] op_sel_hi:[1,0,1]
	v_pk_fma_f32 v[12:13], v[50:51], v[18:19], v[12:13] op_sel_hi:[1,0,1]
	v_pk_fma_f32 v[14:15], v[48:49], v[18:19], v[14:15] op_sel_hi:[1,0,1]
	v_mov_b32_e32 v18, v121
	v_pk_fma_f32 v[2:3], v[58:59], v[128:129], v[2:3] op_sel_hi:[1,0,1]
	v_pk_fma_f32 v[52:53], v[50:51], v[18:19], v[52:53] op_sel_hi:[1,0,1]
	v_pk_fma_f32 v[54:55], v[48:49], v[18:19], v[54:55] op_sel_hi:[1,0,1]
	v_mov_b32_e32 v18, v129
	v_pk_fma_f32 v[50:51], v[50:51], v[18:19], v[2:3] op_sel_hi:[1,0,1]
	s_waitcnt lgkmcnt(0)
	v_pk_add_f32 v[2:3], v[6:7], v[56:57]
	ds_bpermute_b32 v6, v72, v2
	ds_bpermute_b32 v7, v72, v3
	ds_bpermute_b32 v56, v17, v4
	ds_bpermute_b32 v57, v17, v5
	v_pk_fma_f32 v[58:59], v[48:49], v[18:19], v[0:1] op_sel_hi:[1,0,1]
	ds_bpermute_b32 v48, v17, v10
	ds_bpermute_b32 v49, v17, v11
	s_waitcnt lgkmcnt(4)
	v_pk_add_f32 v[0:1], v[2:3], v[6:7]
	s_waitcnt lgkmcnt(2)
	v_pk_add_f32 v[2:3], v[4:5], v[56:57]
	ds_bpermute_b32 v4, v72, v2
	ds_bpermute_b32 v5, v72, v3
	s_waitcnt lgkmcnt(2)
	v_pk_add_f32 v[6:7], v[10:11], v[48:49]
	ds_bpermute_b32 v10, v72, v6
	ds_bpermute_b32 v11, v72, v7
	ds_bpermute_b32 v48, v17, v8
	ds_bpermute_b32 v49, v17, v9
	ds_bpermute_b32 v56, v17, v14
	ds_bpermute_b32 v57, v17, v15
	s_waitcnt lgkmcnt(6)
	v_pk_add_f32 v[2:3], v[2:3], v[4:5]
	s_waitcnt lgkmcnt(4)
	v_pk_add_f32 v[4:5], v[6:7], v[10:11]
	s_waitcnt lgkmcnt(2)
	v_pk_add_f32 v[6:7], v[8:9], v[48:49]
	ds_bpermute_b32 v8, v72, v6
	s_waitcnt lgkmcnt(1)
	v_pk_add_f32 v[14:15], v[14:15], v[56:57]
	ds_bpermute_b32 v9, v72, v7
	ds_bpermute_b32 v48, v72, v14
	ds_bpermute_b32 v49, v72, v15
	ds_bpermute_b32 v56, v17, v12
	ds_bpermute_b32 v57, v17, v13
	s_waitcnt lgkmcnt(4)
	v_pk_add_f32 v[8:9], v[6:7], v[8:9]
	ds_bpermute_b32 v10, v73, v0
	s_waitcnt lgkmcnt(3)
	v_pk_add_f32 v[6:7], v[14:15], v[48:49]
	ds_bpermute_b32 v14, v17, v54
	s_waitcnt lgkmcnt(2)
	v_pk_add_f32 v[12:13], v[12:13], v[56:57]
	ds_bpermute_b32 v15, v17, v55
	ds_bpermute_b32 v56, v17, v52
	ds_bpermute_b32 v57, v17, v53
	ds_bpermute_b32 v48, v72, v12
	ds_bpermute_b32 v49, v72, v13
	s_waitcnt lgkmcnt(4)
	v_pk_add_f32 v[54:55], v[54:55], v[14:15]
	ds_bpermute_b32 v60, v72, v54
	s_waitcnt lgkmcnt(3)
	v_pk_add_f32 v[52:53], v[52:53], v[56:57]
	ds_bpermute_b32 v61, v72, v55
	ds_bpermute_b32 v56, v72, v52
	ds_bpermute_b32 v57, v72, v53
	s_waitcnt lgkmcnt(4)
	v_pk_add_f32 v[14:15], v[12:13], v[48:49]
	ds_bpermute_b32 v11, v73, v1
	s_waitcnt lgkmcnt(3)
	v_pk_add_f32 v[12:13], v[54:55], v[60:61]
	ds_bpermute_b32 v54, v17, v58
	ds_bpermute_b32 v55, v17, v59
	s_waitcnt lgkmcnt(3)
	v_pk_add_f32 v[48:49], v[52:53], v[56:57]
	ds_bpermute_b32 v52, v17, v50
	ds_bpermute_b32 v53, v17, v51
	ds_bpermute_b32 v56, v73, v2
	s_waitcnt lgkmcnt(3)
	v_pk_add_f32 v[54:55], v[58:59], v[54:55]
	ds_bpermute_b32 v58, v72, v54
	ds_bpermute_b32 v59, v72, v55
	s_waitcnt lgkmcnt(3)
	v_pk_add_f32 v[52:53], v[50:51], v[52:53]
	ds_bpermute_b32 v60, v72, v52
	ds_bpermute_b32 v61, v72, v53
	ds_bpermute_b32 v57, v73, v3
	s_waitcnt lgkmcnt(3)
	v_pk_add_f32 v[50:51], v[54:55], v[58:59]
	ds_bpermute_b32 v64, v73, v4
	ds_bpermute_b32 v65, v73, v5
	s_waitcnt lgkmcnt(3)
	v_pk_add_f32 v[52:53], v[52:53], v[60:61]
	ds_bpermute_b32 v70, v73, v8
	ds_bpermute_b32 v71, v73, v9
	ds_bpermute_b32 v66, v73, v6
	ds_bpermute_b32 v67, v73, v7
	ds_bpermute_b32 v68, v73, v14
	ds_bpermute_b32 v69, v73, v15
	ds_bpermute_b32 v60, v73, v12
	ds_bpermute_b32 v61, v73, v13
	ds_bpermute_b32 v62, v73, v48
	ds_bpermute_b32 v63, v73, v49
	ds_bpermute_b32 v54, v73, v50
	ds_bpermute_b32 v55, v73, v51
	ds_bpermute_b32 v58, v73, v52
	ds_bpermute_b32 v59, v73, v53
	s_and_saveexec_b64 s[4:5], vcc
	s_cbranch_execz .LBB0_26
	v_pk_add_f32 v[0:1], v[0:1], v[10:11]
	s_waitcnt lgkmcnt(14)
	v_pk_add_f32 v[2:3], v[2:3], v[56:57]
	ds_write_b128 v75, v[0:3] offset:20480
	v_pk_add_f32 v[0:1], v[4:5], v[64:65]
	s_waitcnt lgkmcnt(13)
	v_pk_add_f32 v[2:3], v[8:9], v[70:71]
	ds_write_b128 v75, v[0:3] offset:20608
	s_waitcnt lgkmcnt(12)
	v_pk_add_f32 v[0:1], v[6:7], v[66:67]
	s_waitcnt lgkmcnt(10)
	v_pk_add_f32 v[2:3], v[14:15], v[68:69]
	ds_write_b128 v75, v[0:3] offset:20736
	s_waitcnt lgkmcnt(9)
	v_pk_add_f32 v[0:1], v[12:13], v[60:61]
	s_waitcnt lgkmcnt(7)
	v_pk_add_f32 v[2:3], v[48:49], v[62:63]
	ds_write_b128 v75, v[0:3] offset:20864
	s_waitcnt lgkmcnt(6)
	v_pk_add_f32 v[0:1], v[50:51], v[54:55]
	s_waitcnt lgkmcnt(4)
	v_pk_add_f32 v[2:3], v[52:53], v[58:59]
	ds_write_b128 v75, v[0:3] offset:20992

; #define LAS __attribute__((address_space(3)))
; __device__ __forceinline__ void transpose_item(const float* W, int K, int N, bf16_t* WT, int n0src, int n0dst, int k0, LAS float* scr, int lane) {
;     float v[32];
; #pragma unroll
;     for (int i = 0; i < 32; ++i) { const int kk = 2 * i + (lane >> 5); v[i] = W[(size_t)(k0 + kk) * N + n0src + (lane & 31)]; }
; #pragma unroll
;     for (int i = 0; i < 32; ++i) { const int kk = 2 * i + (lane >> 5); scr[kk * 33 + (lane & 31)] = v[i]; }
; __device__ __forceinline__ void prologue(const Params& p, LAS unsigned char* lds) {
;     ...
;         for (int it = gw; it < NITEMS; it += NGW) {
;             int r = it;
;             if (r < 4 * I_W1) { const int mi = r / I_W1; r -= mi * I_W1; const int kb = r / 176, nb = r % 176;
;                 transpose_item(p.in[I_FFNWIN] + (size_t)mi * D * NFF1, D, NFF1, (bf16_t*)(ws + WS_W1T + mi * SZ_W1T), paired_src(nb * 32, DFF), nb * 32, kb * 64, scr, lane); continue; }
;             r -= 4 * I_W1;
;             if (r < 4 * I_W2) { const int mi = r / I_W2; r -= mi * I_W2; const int kb = r / 32, nb = r % 32;
;                 transpose_item(p.in[I_FFNWOUT] + (size_t)mi * DFF * D, DFF, D, (bf16_t*)(ws + WS_W2T + mi * SZ_W2T), nb * 32, nb * 32, kb * 64, scr, lane); continue; }
;             r -= 4 * I_W2;
;             if (r < I_AB) { const int kb = r / 80, nb = r % 80; const int nd = nb * 32, nsrc = nd < 1024 ? paired_src(nd, 512) : nd;
;                 transpose_item(p.in[I_ABWIN], D, NAB, (bf16_t*)(ws + WS_WABT), nsrc, nd, kb * 64, scr, lane); continue; }
;             r -= I_AB;
;             if (r < I_SQ) { const int kb = r / 32, nb = r % 32; transpose_item(p.in[I_ABWOUT], D, D, (bf16_t*)(ws + WS_WOT), nb * 32, nb * 32, kb * 64, scr, lane); continue; }
;             r -= I_SQ;
;             { const int kb = r / 32, nb = r % 32; transpose_item(p.in[I_FNETW], D, D, (bf16_t*)(ws + WS_WFT), nb * 32, nb * 32, kb * 64, scr, lane); }
.LBB0_31:
	v_cmp_lt_i32_e32 vcc, s22, v39
	s_and_saveexec_b64 s[8:9], vcc
	s_xor_b64 s[8:9], exec, s[8:9]
	s_cbranch_execz .LBB0_47
	v_cmp_lt_u32_e32 vcc, s23, v39
	s_and_saveexec_b64 s[10:11], vcc
	s_xor_b64 s[10:11], exec, s[10:11]
	s_cbranch_execz .LBB0_44
	v_cmp_lt_u32_e32 vcc, s24, v39
	s_and_saveexec_b64 s[12:13], vcc
	s_xor_b64 s[12:13], exec, s[12:13]
	s_cbranch_execz .LBB0_39
	v_and_b32_e32 v18, 0x3e0, v28
	v_cmp_lt_u32_e32 vcc, s25, v39
	v_lshlrev_b32_e32 v0, 2, v18
	v_or_b32_e32 v41, v18, v23
	v_or_b32_e32 v40, v18, v25
	v_or_b32_e32 v21, v18, v26
	v_or_b32_e32 v20, v18, v27
	s_and_saveexec_b64 s[14:15], vcc
	s_xor_b64 s[14:15], exec, s[14:15]
	s_cbranch_execz .LBB0_36
	v_and_b32_e32 v18, 0x7fffffc0, v29
	v_add_u32_e32 v18, 0xffff6e00, v18
	v_or_b32_e32 v42, v18, v17
	v_lshl_add_u64 v[44:45], v[10:11], 0, v[0:1]
	v_or_b32_e32 v0, 2, v42
	v_lshlrev_b64 v[48:49], 12, v[0:1]
	v_or_b32_e32 v0, 4, v42
	v_lshlrev_b64 v[50:51], 12, v[0:1]
	v_or_b32_e32 v0, 6, v42
	v_lshlrev_b64 v[52:53], 12, v[0:1]
	v_or_b32_e32 v0, 8, v42
	v_lshlrev_b64 v[54:55], 12, v[0:1]
	v_or_b32_e32 v0, 10, v42
	v_mov_b32_e32 v43, v1
	v_lshlrev_b64 v[56:57], 12, v[0:1]
	v_or_b32_e32 v0, 12, v42
	v_lshlrev_b64 v[46:47], 12, v[42:43]
	v_lshlrev_b64 v[58:59], 12, v[0:1]
	v_or_b32_e32 v0, 14, v42
	v_lshl_add_u64 v[46:47], v[44:45], 0, v[46:47]
	v_lshlrev_b64 v[60:61], 12, v[0:1]
	v_or_b32_e32 v0, 16, v42
	v_lshl_add_u64 v[48:49], v[44:45], 0, v[48:49]
	v_lshl_add_u64 v[50:51], v[44:45], 0, v[50:51]
	v_lshl_add_u64 v[52:53], v[44:45], 0, v[52:53]
	v_lshl_add_u64 v[54:55], v[44:45], 0, v[54:55]
	v_lshl_add_u64 v[56:57], v[44:45], 0, v[56:57]
	v_lshl_add_u64 v[58:59], v[44:45], 0, v[58:59]
	v_lshl_add_u64 v[60:61], v[44:45], 0, v[60:61]
	global_load_dword v19, v[46:47], off nt
	global_load_dword v62, v[48:49], off nt
	global_load_dword v63, v[50:51], off nt
	global_load_dword v64, v[52:53], off nt
	global_load_dword v65, v[54:55], off nt
	global_load_dword v66, v[56:57], off nt
	global_load_dword v67, v[58:59], off nt
	global_load_dword v68, v[60:61], off nt
	v_lshlrev_b64 v[46:47], 12, v[0:1]
	v_or_b32_e32 v0, 18, v42
	v_lshlrev_b64 v[48:49], 12, v[0:1]
	v_or_b32_e32 v0, 20, v42
	v_lshlrev_b64 v[50:51], 12, v[0:1]
	v_or_b32_e32 v0, 22, v42
	v_lshlrev_b64 v[52:53], 12, v[0:1]
	v_or_b32_e32 v0, 24, v42
	v_lshlrev_b64 v[54:55], 12, v[0:1]
	v_or_b32_e32 v0, 26, v42
	v_lshlrev_b64 v[56:57], 12, v[0:1]
	v_or_b32_e32 v0, 28, v42
	v_lshlrev_b64 v[58:59], 12, v[0:1]
	v_or_b32_e32 v0, 30, v42
	v_lshl_add_u64 v[46:47], v[44:45], 0, v[46:47]
	v_lshlrev_b64 v[60:61], 12, v[0:1]
	v_or_b32_e32 v0, 32, v42
	v_lshl_add_u64 v[48:49], v[44:45], 0, v[48:49]
	v_lshl_add_u64 v[50:51], v[44:45], 0, v[50:51]
	v_lshl_add_u64 v[52:53], v[44:45], 0, v[52:53]
	v_lshl_add_u64 v[54:55], v[44:45], 0, v[54:55]
	v_lshl_add_u64 v[56:57], v[44:45], 0, v[56:57]
	v_lshl_add_u64 v[58:59], v[44:45], 0, v[58:59]
	v_lshl_add_u64 v[60:61], v[44:45], 0, v[60:61]
	global_load_dword v69, v[46:47], off nt
	global_load_dword v70, v[48:49], off nt
	global_load_dword v71, v[50:51], off nt
	global_load_dword v72, v[52:53], off nt
	global_load_dword v73, v[54:55], off nt
	global_load_dword v74, v[56:57], off nt
	global_load_dword v75, v[58:59], off nt
	global_load_dword v76, v[60:61], off nt
	v_lshlrev_b64 v[46:47], 12, v[0:1]
	v_or_b32_e32 v0, 34, v42
	v_lshlrev_b64 v[48:49], 12, v[0:1]
	v_or_b32_e32 v0, 36, v42
	v_lshlrev_b64 v[50:51], 12, v[0:1]
	v_or_b32_e32 v0, 38, v42
	v_lshlrev_b64 v[52:53], 12, v[0:1]
	v_or_b32_e32 v0, 40, v42
	v_lshlrev_b64 v[54:55], 12, v[0:1]
	v_or_b32_e32 v0, 42, v42
	v_lshlrev_b64 v[56:57], 12, v[0:1]
	v_or_b32_e32 v0, 44, v42
	v_lshlrev_b64 v[58:59], 12, v[0:1]
	v_or_b32_e32 v0, 46, v42
	v_lshlrev_b64 v[60:61], 12, v[0:1]
	v_lshl_add_u64 v[46:47], v[44:45], 0, v[46:47]
	v_lshl_add_u64 v[60:61], v[44:45], 0, v[60:61]
	v_or_b32_e32 v0, 48, v42
	v_lshl_add_u64 v[48:49], v[44:45], 0, v[48:49]
	v_lshl_add_u64 v[50:51], v[44:45], 0, v[50:51]
	v_lshl_add_u64 v[52:53], v[44:45], 0, v[52:53]
	v_lshl_add_u64 v[54:55], v[44:45], 0, v[54:55]
	v_lshl_add_u64 v[56:57], v[44:45], 0, v[56:57]
	v_lshl_add_u64 v[58:59], v[44:45], 0, v[58:59]
	global_load_dword v77, v[46:47], off nt
	global_load_dword v78, v[48:49], off nt
	global_load_dword v79, v[50:51], off nt
	global_load_dword v80, v[52:53], off nt
	global_load_dword v81, v[54:55], off nt
	global_load_dword v82, v[56:57], off nt
	global_load_dword v83, v[58:59], off nt
	s_nop 0
	global_load_dword v60, v[60:61], off nt
	v_lshlrev_b64 v[46:47], 12, v[0:1]
	v_or_b32_e32 v0, 50, v42
	v_lshlrev_b64 v[48:49], 12, v[0:1]
	v_or_b32_e32 v0, 52, v42
	v_lshlrev_b64 v[50:51], 12, v[0:1]
	v_or_b32_e32 v0, 54, v42
	v_lshlrev_b64 v[52:53], 12, v[0:1]
	v_or_b32_e32 v0, 56, v42
	v_lshlrev_b64 v[54:55], 12, v[0:1]
	v_or_b32_e32 v0, 58, v42
	v_lshlrev_b64 v[56:57], 12, v[0:1]
	v_or_b32_e32 v0, 60, v42
	v_lshlrev_b64 v[58:59], 12, v[0:1]
	v_or_b32_e32 v0, 62, v42
	v_lshlrev_b64 v[42:43], 12, v[0:1]
	v_lshl_add_u64 v[46:47], v[44:45], 0, v[46:47]
	v_lshl_add_u64 v[48:49], v[44:45], 0, v[48:49]
	v_lshl_add_u64 v[42:43], v[44:45], 0, v[42:43]
	v_lshl_add_u64 v[50:51], v[44:45], 0, v[50:51]
	v_lshl_add_u64 v[52:53], v[44:45], 0, v[52:53]
	v_lshl_add_u64 v[54:55], v[44:45], 0, v[54:55]
	v_lshl_add_u64 v[56:57], v[44:45], 0, v[56:57]
	v_lshl_add_u64 v[58:59], v[44:45], 0, v[58:59]
	global_load_dword v0, v[46:47], off nt
	global_load_dword v44, v[48:49], off nt
	global_load_dword v45, v[50:51], off nt
	s_nop 0
	global_load_dword v46, v[52:53], off nt
	global_load_dword v47, v[54:55], off nt
	global_load_dword v48, v[56:57], off nt
	global_load_dword v49, v[58:59], off nt
	s_nop 0
	global_load_dword v42, v[42:43], off nt
	s_waitcnt vmcnt(30)
; #define LAS __attribute__((address_space(3)))
; __device__ __forceinline__ unsigned cvt_pk_bf16(float lo, float hi) { unsigned r; asm volatile("v_cvt_pk_bf16_f32 %0, %1, %2" : "=v"(r) : "v"(lo), "v"(hi)); return r; }
; #define ST16(grp, p, v) do { if ((NTG >> (grp)) & 1) NT16(p, v); else PL16(p, v); } while (0)
; __device__ __forceinline__ void transpose_item(const float* W, int K, int N, bf16_t* WT, int n0src, int n0dst, int k0, LAS float* scr, int lane) {
;     float v[32];
; #pragma unroll
;     for (int i = 0; i < 32; ++i) { const int kk = 2 * i + (lane >> 5); v[i] = W[(size_t)(k0 + kk) * N + n0src + (lane & 31)]; }
; #pragma unroll
;     for (int i = 0; i < 32; ++i) { const int kk = 2 * i + (lane >> 5); scr[kk * 33 + (lane & 31)] = v[i]; }
;     asm volatile("s_waitcnt lgkmcnt(0)" ::: "memory");
;     const int c = lane & 7;
; #pragma unroll
;     for (int j = 0; j < 4; ++j) { const int n = (lane >> 3) + 8 * j; const LAS float* s = scr + (8 * c) * 33 + n;
;         u32x4 o; o.x = cvt_pk_bf16(s[0 * 33], s[1 * 33]); o.y = cvt_pk_bf16(s[2 * 33], s[3 * 33]); o.z = cvt_pk_bf16(s[4 * 33], s[5 * 33]); o.w = cvt_pk_bf16(s[6 * 33], s[7 * 33]);
;         ST16(6, WT + (size_t)(n0dst + n) * K + k0 + 8 * c, o); }
;     asm volatile("s_waitcnt lgkmcnt(0)" ::: "memory");
; }
; __device__ __forceinline__ void prologue(const Params& p, LAS unsigned char* lds) {
;     ...
;             if (r < I_SQ) { const int kb = r / 32, nb = r % 32; transpose_item(p.in[I_ABWOUT], D, D, (bf16_t*)(ws + WS_WOT), nb * 32, nb * 32, kb * 64, scr, lane); continue; }
;             r -= I_SQ;
;             { const int kb = r / 32, nb = r % 32; transpose_item(p.in[I_FNETW], D, D, (bf16_t*)(ws + WS_WFT), nb * 32, nb * 32, kb * 64, scr, lane); }
	ds_write2_b32 v22, v19, v62 offset1:66
	s_waitcnt vmcnt(28)
	ds_write2_b32 v22, v63, v64 offset0:132 offset1:198
	s_waitcnt vmcnt(26)
	ds_write2_b32 v30, v65, v66 offset0:8 offset1:74
	s_waitcnt vmcnt(24)
	ds_write2_b32 v30, v67, v68 offset0:140 offset1:206
	s_waitcnt vmcnt(22)
	ds_write2_b32 v31, v69, v70 offset0:16 offset1:82
	s_waitcnt vmcnt(20)
	ds_write2_b32 v31, v71, v72 offset0:148 offset1:214
	s_waitcnt vmcnt(18)
	ds_write2_b32 v32, v73, v74 offset0:24 offset1:90
	s_waitcnt vmcnt(16)
	ds_write2_b32 v32, v75, v76 offset0:156 offset1:222
	s_waitcnt vmcnt(14)
	ds_write2_b32 v33, v77, v78 offset0:32 offset1:98
	s_waitcnt vmcnt(12)
	ds_write2_b32 v33, v79, v80 offset0:164 offset1:230
	s_waitcnt vmcnt(10)
	ds_write2_b32 v34, v81, v82 offset0:40 offset1:106
	s_waitcnt vmcnt(8)
	ds_write2_b32 v34, v83, v60 offset0:172 offset1:238
	s_waitcnt vmcnt(6)
	ds_write2_b32 v35, v0, v44 offset0:48 offset1:114
	s_waitcnt vmcnt(4)
	ds_write2_b32 v35, v45, v46 offset0:180 offset1:246
	s_waitcnt vmcnt(2)
	ds_write2_b32 v36, v47, v48 offset0:56 offset1:122
	s_waitcnt vmcnt(0)
	ds_write2_b32 v36, v49, v42 offset0:188 offset1:254
	s_waitcnt lgkmcnt(0)
	ds_read2_b32 v[42:43], v24 offset1:33
	s_waitcnt lgkmcnt(0)
	v_cvt_pk_bf16_f32 v42, v42, v43
	ds_read2_b32 v[44:45], v24 offset0:66 offset1:99
	v_mov_b32_e32 v19, v1
	s_waitcnt lgkmcnt(0)
	v_cvt_pk_bf16_f32 v43, v44, v45
	ds_read2_b32 v[44:45], v24 offset0:132 offset1:165
	v_lshl_add_u64 v[18:19], v[18:19], 1, v[4:5]
	v_lshlrev_b32_e32 v0, 11, v41
	s_waitcnt lgkmcnt(0)
	v_cvt_pk_bf16_f32 v44, v44, v45
	ds_read2_b32 v[46:47], v24 offset0:198 offset1:231
	s_waitcnt lgkmcnt(0)
	v_cvt_pk_bf16_f32 v45, v46, v47
	v_lshl_add_u64 v[48:49], v[18:19], 0, v[0:1]
	ds_read2_b32 v[46:47], v24 offset0:8 offset1:41
	global_store_dwordx4 v[48:49], v[42:45], off
	v_lshlrev_b32_e32 v0, 11, v40
	v_lshl_add_u64 v[40:41], v[18:19], 0, v[0:1]
	s_waitcnt lgkmcnt(0)
	v_cvt_pk_bf16_f32 v42, v46, v47
	ds_read2_b32 v[44:45], v24 offset0:74 offset1:107
	s_waitcnt lgkmcnt(0)
	v_cvt_pk_bf16_f32 v43, v44, v45
	ds_read2_b32 v[44:45], v24 offset0:140 offset1:173
	s_waitcnt lgkmcnt(0)
	v_cvt_pk_bf16_f32 v44, v44, v45
	ds_read2_b32 v[46:47], v24 offset0:206 offset1:239
	s_waitcnt lgkmcnt(0)
	v_cvt_pk_bf16_f32 v45, v46, v47
	ds_read2_b32 v[46:47], v24 offset0:16 offset1:49
	global_store_dwordx4 v[40:41], v[42:45], off
	s_waitcnt lgkmcnt(0)
	v_cvt_pk_bf16_f32 v40, v46, v47
	ds_read2_b32 v[42:43], v24 offset0:82 offset1:115
	s_waitcnt lgkmcnt(0)
	v_cvt_pk_bf16_f32 v41, v42, v43
	ds_read2_b32 v[42:43], v24 offset0:148 offset1:181
	v_lshlrev_b32_e32 v0, 11, v21
	s_waitcnt lgkmcnt(0)
	v_cvt_pk_bf16_f32 v42, v42, v43
	ds_read2_b32 v[44:45], v24 offset0:214 offset1:247
	s_waitcnt lgkmcnt(0)
	v_cvt_pk_bf16_f32 v43, v44, v45
	v_lshl_add_u64 v[46:47], v[18:19], 0, v[0:1]
	ds_read2_b32 v[44:45], v24 offset0:24 offset1:57
	global_store_dwordx4 v[46:47], v[40:43], off
	v_lshlrev_b32_e32 v0, 11, v20
	v_lshl_add_u64 v[18:19], v[18:19], 0, v[0:1]
	s_waitcnt lgkmcnt(0)
	v_cvt_pk_bf16_f32 v40, v44, v45
	ds_read2_b32 v[42:43], v24 offset0:90 offset1:123
	s_waitcnt lgkmcnt(0)
	v_cvt_pk_bf16_f32 v41, v42, v43
	ds_read2_b32 v[42:43], v24 offset0:156 offset1:189
	s_waitcnt lgkmcnt(0)
	v_cvt_pk_bf16_f32 v42, v42, v43
	ds_read2_b32 v[44:45], v24 offset0:222 offset1:255
	s_waitcnt lgkmcnt(0)
	v_cvt_pk_bf16_f32 v43, v44, v45
	global_store_dwordx4 v[18:19], v[40:43], off
	s_waitcnt lgkmcnt(0)
.LBB0_36:
	s_andn2_saveexec_b64 s[14:15], s[14:15]
	s_cbranch_execz .LBB0_38
	v_and_b32_e32 v18, 0xffc0, v29
	v_add_u32_e32 v18, 0xffff7200, v18
	v_or_b32_e32 v42, v18, v17
	v_lshl_add_u64 v[44:45], v[12:13], 0, v[0:1]
	v_or_b32_e32 v0, 2, v42
	v_lshlrev_b64 v[48:49], 12, v[0:1]
	v_or_b32_e32 v0, 4, v42
	v_lshlrev_b64 v[50:51], 12, v[0:1]
	v_or_b32_e32 v0, 6, v42
	v_lshlrev_b64 v[52:53], 12, v[0:1]
	v_or_b32_e32 v0, 8, v42
	v_lshlrev_b64 v[54:55], 12, v[0:1]
	v_or_b32_e32 v0, 10, v42
	v_mov_b32_e32 v43, v1
	v_lshlrev_b64 v[56:57], 12, v[0:1]
	v_or_b32_e32 v0, 12, v42
	v_lshlrev_b64 v[46:47], 12, v[42:43]
	v_lshlrev_b64 v[58:59], 12, v[0:1]
	v_or_b32_e32 v0, 14, v42
	v_lshl_add_u64 v[46:47], v[44:45], 0, v[46:47]
	v_lshlrev_b64 v[60:61], 12, v[0:1]
	v_or_b32_e32 v0, 16, v42
	v_lshl_add_u64 v[48:49], v[44:45], 0, v[48:49]
	v_lshl_add_u64 v[50:51], v[44:45], 0, v[50:51]
	v_lshl_add_u64 v[52:53], v[44:45], 0, v[52:53]
	v_lshl_add_u64 v[54:55], v[44:45], 0, v[54:55]
	v_lshl_add_u64 v[56:57], v[44:45], 0, v[56:57]
	v_lshl_add_u64 v[58:59], v[44:45], 0, v[58:59]
	v_lshl_add_u64 v[60:61], v[44:45], 0, v[60:61]
	global_load_dword v19, v[46:47], off nt
	global_load_dword v62, v[48:49], off nt
	global_load_dword v63, v[50:51], off nt
	global_load_dword v64, v[52:53], off nt
	global_load_dword v65, v[54:55], off nt
	global_load_dword v66, v[56:57], off nt
	global_load_dword v67, v[58:59], off nt
	global_load_dword v68, v[60:61], off nt
	v_lshlrev_b64 v[46:47], 12, v[0:1]
	v_or_b32_e32 v0, 18, v42
	v_lshlrev_b64 v[48:49], 12, v[0:1]
	v_or_b32_e32 v0, 20, v42
	v_lshlrev_b64 v[50:51], 12, v[0:1]
	v_or_b32_e32 v0, 22, v42
	v_lshlrev_b64 v[52:53], 12, v[0:1]
	v_or_b32_e32 v0, 24, v42
	v_lshlrev_b64 v[54:55], 12, v[0:1]
	v_or_b32_e32 v0, 26, v42
	v_lshlrev_b64 v[56:57], 12, v[0:1]
	v_or_b32_e32 v0, 28, v42
	v_lshlrev_b64 v[58:59], 12, v[0:1]
	v_or_b32_e32 v0, 30, v42
	v_lshl_add_u64 v[46:47], v[44:45], 0, v[46:47]
	v_lshlrev_b64 v[60:61], 12, v[0:1]
	v_or_b32_e32 v0, 32, v42
	v_lshl_add_u64 v[48:49], v[44:45], 0, v[48:49]
	v_lshl_add_u64 v[50:51], v[44:45], 0, v[50:51]
	v_lshl_add_u64 v[52:53], v[44:45], 0, v[52:53]
	v_lshl_add_u64 v[54:55], v[44:45], 0, v[54:55]
	v_lshl_add_u64 v[56:57], v[44:45], 0, v[56:57]
; #define LAS __attribute__((address_space(3)))
; __device__ __forceinline__ unsigned cvt_pk_bf16(float lo, float hi) { unsigned r; asm volatile("v_cvt_pk_bf16_f32 %0, %1, %2" : "=v"(r) : "v"(lo), "v"(hi)); return r; }
; #define ST16(grp, p, v) do { if ((NTG >> (grp)) & 1) NT16(p, v); else PL16(p, v); } while (0)
; __device__ __forceinline__ void transpose_item(const float* W, int K, int N, bf16_t* WT, int n0src, int n0dst, int k0, LAS float* scr, int lane) {
;     float v[32];
; #pragma unroll
;     for (int i = 0; i < 32; ++i) { const int kk = 2 * i + (lane >> 5); v[i] = W[(size_t)(k0 + kk) * N + n0src + (lane & 31)]; }
; #pragma unroll
;     for (int i = 0; i < 32; ++i) { const int kk = 2 * i + (lane >> 5); scr[kk * 33 + (lane & 31)] = v[i]; }
;     asm volatile("s_waitcnt lgkmcnt(0)" ::: "memory");
;     const int c = lane & 7;
; #pragma unroll
;     for (int j = 0; j < 4; ++j) { const int n = (lane >> 3) + 8 * j; const LAS float* s = scr + (8 * c) * 33 + n;
;         u32x4 o; o.x = cvt_pk_bf16(s[0 * 33], s[1 * 33]); o.y = cvt_pk_bf16(s[2 * 33], s[3 * 33]); o.z = cvt_pk_bf16(s[4 * 33], s[5 * 33]); o.w = cvt_pk_bf16(s[6 * 33], s[7 * 33]);
;         ST16(6, WT + (size_t)(n0dst + n) * K + k0 + 8 * c, o); }
;     asm volatile("s_waitcnt lgkmcnt(0)" ::: "memory");
; }
	v_lshl_add_u64 v[58:59], v[44:45], 0, v[58:59]
	v_lshl_add_u64 v[60:61], v[44:45], 0, v[60:61]
	global_load_dword v69, v[46:47], off nt
	global_load_dword v70, v[48:49], off nt
	global_load_dword v71, v[50:51], off nt
	global_load_dword v72, v[52:53], off nt
	global_load_dword v73, v[54:55], off nt
	global_load_dword v74, v[56:57], off nt
	global_load_dword v75, v[58:59], off nt
	global_load_dword v76, v[60:61], off nt
	v_lshlrev_b64 v[46:47], 12, v[0:1]
	v_or_b32_e32 v0, 34, v42
	v_lshlrev_b64 v[48:49], 12, v[0:1]
	v_or_b32_e32 v0, 36, v42
	v_lshlrev_b64 v[50:51], 12, v[0:1]
	v_or_b32_e32 v0, 38, v42
	v_lshlrev_b64 v[52:53], 12, v[0:1]
	v_or_b32_e32 v0, 40, v42
	v_lshlrev_b64 v[54:55], 12, v[0:1]
	v_or_b32_e32 v0, 42, v42
	v_lshlrev_b64 v[56:57], 12, v[0:1]
	v_or_b32_e32 v0, 44, v42
	v_lshlrev_b64 v[58:59], 12, v[0:1]
	v_or_b32_e32 v0, 46, v42
	v_lshlrev_b64 v[60:61], 12, v[0:1]
	v_lshl_add_u64 v[46:47], v[44:45], 0, v[46:47]
	v_lshl_add_u64 v[60:61], v[44:45], 0, v[60:61]
	v_or_b32_e32 v0, 48, v42
	v_lshl_add_u64 v[48:49], v[44:45], 0, v[48:49]
	v_lshl_add_u64 v[50:51], v[44:45], 0, v[50:51]
	v_lshl_add_u64 v[52:53], v[44:45], 0, v[52:53]
	v_lshl_add_u64 v[54:55], v[44:45], 0, v[54:55]
	v_lshl_add_u64 v[56:57], v[44:45], 0, v[56:57]
	v_lshl_add_u64 v[58:59], v[44:45], 0, v[58:59]
	global_load_dword v77, v[46:47], off nt
	global_load_dword v78, v[48:49], off nt
	global_load_dword v79, v[50:51], off nt
	global_load_dword v80, v[52:53], off nt
	global_load_dword v81, v[54:55], off nt
	global_load_dword v82, v[56:57], off nt
	global_load_dword v83, v[58:59], off nt
	s_nop 0
	global_load_dword v60, v[60:61], off nt
	v_lshlrev_b64 v[46:47], 12, v[0:1]
	v_or_b32_e32 v0, 50, v42
	v_lshlrev_b64 v[48:49], 12, v[0:1]
	v_or_b32_e32 v0, 52, v42
	v_lshlrev_b64 v[50:51], 12, v[0:1]
	v_or_b32_e32 v0, 54, v42
	v_lshlrev_b64 v[52:53], 12, v[0:1]
	v_or_b32_e32 v0, 56, v42
	v_lshlrev_b64 v[54:55], 12, v[0:1]
	v_or_b32_e32 v0, 58, v42
	v_lshlrev_b64 v[56:57], 12, v[0:1]
	v_or_b32_e32 v0, 60, v42
	v_lshlrev_b64 v[58:59], 12, v[0:1]
	v_or_b32_e32 v0, 62, v42
	v_lshlrev_b64 v[42:43], 12, v[0:1]
	v_lshl_add_u64 v[46:47], v[44:45], 0, v[46:47]
	v_lshl_add_u64 v[48:49], v[44:45], 0, v[48:49]
	v_lshl_add_u64 v[42:43], v[44:45], 0, v[42:43]
	v_lshl_add_u64 v[50:51], v[44:45], 0, v[50:51]
	v_lshl_add_u64 v[52:53], v[44:45], 0, v[52:53]
	v_lshl_add_u64 v[54:55], v[44:45], 0, v[54:55]
	v_lshl_add_u64 v[56:57], v[44:45], 0, v[56:57]
	v_lshl_add_u64 v[58:59], v[44:45], 0, v[58:59]
	global_load_dword v0, v[46:47], off nt
	global_load_dword v44, v[48:49], off nt
	global_load_dword v45, v[50:51], off nt
	s_nop 0
	global_load_dword v46, v[52:53], off nt
	global_load_dword v47, v[54:55], off nt
	global_load_dword v48, v[56:57], off nt
	global_load_dword v49, v[58:59], off nt
	s_nop 0
	global_load_dword v42, v[42:43], off nt
	s_waitcnt vmcnt(30)
	ds_write2_b32 v22, v19, v62 offset1:66
	s_waitcnt vmcnt(28)
	ds_write2_b32 v22, v63, v64 offset0:132 offset1:198
	s_waitcnt vmcnt(26)
	ds_write2_b32 v30, v65, v66 offset0:8 offset1:74
	s_waitcnt vmcnt(24)
	ds_write2_b32 v30, v67, v68 offset0:140 offset1:206
	s_waitcnt vmcnt(22)
	ds_write2_b32 v31, v69, v70 offset0:16 offset1:82
	s_waitcnt vmcnt(20)
	ds_write2_b32 v31, v71, v72 offset0:148 offset1:214
	s_waitcnt vmcnt(18)
	ds_write2_b32 v32, v73, v74 offset0:24 offset1:90
	s_waitcnt vmcnt(16)
	ds_write2_b32 v32, v75, v76 offset0:156 offset1:222
	s_waitcnt vmcnt(14)
	ds_write2_b32 v33, v77, v78 offset0:32 offset1:98
	s_waitcnt vmcnt(12)
	ds_write2_b32 v33, v79, v80 offset0:164 offset1:230
	s_waitcnt vmcnt(10)
	ds_write2_b32 v34, v81, v82 offset0:40 offset1:106
	s_waitcnt vmcnt(8)
	ds_write2_b32 v34, v83, v60 offset0:172 offset1:238
	s_waitcnt vmcnt(6)
	ds_write2_b32 v35, v0, v44 offset0:48 offset1:114
	s_waitcnt vmcnt(4)
	ds_write2_b32 v35, v45, v46 offset0:180 offset1:246
	s_waitcnt vmcnt(2)
	ds_write2_b32 v36, v47, v48 offset0:56 offset1:122
	s_waitcnt vmcnt(0)
	ds_write2_b32 v36, v49, v42 offset0:188 offset1:254
	s_waitcnt lgkmcnt(0)
	ds_read2_b32 v[42:43], v24 offset1:33
	s_waitcnt lgkmcnt(0)
	v_cvt_pk_bf16_f32 v42, v42, v43
	ds_read2_b32 v[44:45], v24 offset0:66 offset1:99
	v_mov_b32_e32 v19, v1
	s_waitcnt lgkmcnt(0)
	v_cvt_pk_bf16_f32 v43, v44, v45
	ds_read2_b32 v[44:45], v24 offset0:132 offset1:165
	v_lshl_add_u64 v[18:19], v[18:19], 1, v[6:7]
	v_lshlrev_b32_e32 v0, 11, v41
	s_waitcnt lgkmcnt(0)
	v_cvt_pk_bf16_f32 v44, v44, v45
	ds_read2_b32 v[46:47], v24 offset0:198 offset1:231
	s_waitcnt lgkmcnt(0)
	v_cvt_pk_bf16_f32 v45, v46, v47
	v_lshl_add_u64 v[48:49], v[18:19], 0, v[0:1]
	ds_read2_b32 v[46:47], v24 offset0:8 offset1:41
	global_store_dwordx4 v[48:49], v[42:45], off
	v_lshlrev_b32_e32 v0, 11, v40
	v_lshl_add_u64 v[40:41], v[18:19], 0, v[0:1]
	s_waitcnt lgkmcnt(0)
	v_cvt_pk_bf16_f32 v42, v46, v47
	ds_read2_b32 v[44:45], v24 offset0:74 offset1:107
	s_waitcnt lgkmcnt(0)
	v_cvt_pk_bf16_f32 v43, v44, v45
	ds_read2_b32 v[44:45], v24 offset0:140 offset1:173
	s_waitcnt lgkmcnt(0)
	v_cvt_pk_bf16_f32 v44, v44, v45
	ds_read2_b32 v[46:47], v24 offset0:206 offset1:239
	s_waitcnt lgkmcnt(0)
	v_cvt_pk_bf16_f32 v45, v46, v47
	ds_read2_b32 v[46:47], v24 offset0:16 offset1:49
	global_store_dwordx4 v[40:41], v[42:45], off
	s_waitcnt lgkmcnt(0)
	v_cvt_pk_bf16_f32 v40, v46, v47
	ds_read2_b32 v[42:43], v24 offset0:82 offset1:115
	s_waitcnt lgkmcnt(0)
	v_cvt_pk_bf16_f32 v41, v42, v43
	ds_read2_b32 v[42:43], v24 offset0:148 offset1:181
	v_lshlrev_b32_e32 v0, 11, v21
	s_waitcnt lgkmcnt(0)
	v_cvt_pk_bf16_f32 v42, v42, v43
	ds_read2_b32 v[44:45], v24 offset0:214 offset1:247
	s_waitcnt lgkmcnt(0)
	v_cvt_pk_bf16_f32 v43, v44, v45
	v_lshl_add_u64 v[46:47], v[18:19], 0, v[0:1]
	ds_read2_b32 v[44:45], v24 offset0:24 offset1:57
	global_store_dwordx4 v[46:47], v[40:43], off
	v_lshlrev_b32_e32 v0, 11, v20
	v_lshl_add_u64 v[18:19], v[18:19], 0, v[0:1]
	s_waitcnt lgkmcnt(0)
	v_cvt_pk_bf16_f32 v40, v44, v45
	ds_read2_b32 v[42:43], v24 offset0:90 offset1:123
	s_waitcnt lgkmcnt(0)
	v_cvt_pk_bf16_f32 v41, v42, v43
	ds_read2_b32 v[42:43], v24 offset0:156 offset1:189
	s_waitcnt lgkmcnt(0)
	v_cvt_pk_bf16_f32 v42, v42, v43
	ds_read2_b32 v[44:45], v24 offset0:222 offset1:255
	s_waitcnt lgkmcnt(0)
	v_cvt_pk_bf16_f32 v43, v44, v45
	global_store_dwordx4 v[18:19], v[40:43], off
	s_waitcnt lgkmcnt(0)

; #define LAS __attribute__((address_space(3)))
; __device__ __forceinline__ unsigned cvt_pk_bf16(float lo, float hi) { unsigned r; asm volatile("v_cvt_pk_bf16_f32 %0, %1, %2" : "=v"(r) : "v"(lo), "v"(hi)); return r; }
; #define ST16(grp, p, v) do { if ((NTG >> (grp)) & 1) NT16(p, v); else PL16(p, v); } while (0)
; __device__ __forceinline__ void transpose_item(const float* W, int K, int N, bf16_t* WT, int n0src, int n0dst, int k0, LAS float* scr, int lane) {
;     float v[32];
; #pragma unroll
;     for (int i = 0; i < 32; ++i) { const int kk = 2 * i + (lane >> 5); v[i] = W[(size_t)(k0 + kk) * N + n0src + (lane & 31)]; }
; #pragma unroll
;     for (int i = 0; i < 32; ++i) { const int kk = 2 * i + (lane >> 5); scr[kk * 33 + (lane & 31)] = v[i]; }
;     asm volatile("s_waitcnt lgkmcnt(0)" ::: "memory");
;     const int c = lane & 7;
; #pragma unroll
;     for (int j = 0; j < 4; ++j) { const int n = (lane >> 3) + 8 * j; const LAS float* s = scr + (8 * c) * 33 + n;
;         u32x4 o; o.x = cvt_pk_bf16(s[0 * 33], s[1 * 33]); o.y = cvt_pk_bf16(s[2 * 33], s[3 * 33]); o.z = cvt_pk_bf16(s[4 * 33], s[5 * 33]); o.w = cvt_pk_bf16(s[6 * 33], s[7 * 33]);
;         ST16(6, WT + (size_t)(n0dst + n) * K + k0 + 8 * c, o); }
;     asm volatile("s_waitcnt lgkmcnt(0)" ::: "memory");
; }
; __device__ __forceinline__ void prologue(const Params& p, LAS unsigned char* lds) {
;     ...
;             if (r < I_AB) { const int kb = r / 80, nb = r % 80; const int nd = nb * 32, nsrc = nd < 1024 ? paired_src(nd, 512) : nd;
;                 transpose_item(p.in[I_ABWIN], D, NAB, (bf16_t*)(ws + WS_WABT), nsrc, nd, kb * 64, scr, lane); continue; }
.LBB0_39:
	s_andn2_saveexec_b64 s[12:13], s[12:13]
	s_cbranch_execz .LBB0_43
	v_add_u16_e32 v18, 0xbe00, v39
	v_mul_u32_u24_e32 v0, 0xcccd, v18
	v_lshrrev_b32_e32 v0, 22, v0
	v_mul_lo_u16_e32 v19, 0x50, v0
	v_sub_u16_e32 v19, v18, v19
	v_lshlrev_b16_e32 v18, 5, v19
	v_cmp_gt_u16_e32 vcc, 32, v19
	v_mov_b32_e32 v19, v18
	s_and_saveexec_b64 s[14:15], vcc
	v_lshrrev_b32_e32 v20, 1, v18
	v_and_b32_e32 v19, 0xe0, v18
	v_and_b32_e32 v20, 0x180, v20
	v_or_b32_e32 v21, v20, v19
	v_add3_u32 v20, v19, v20, s27
	v_cmp_gt_u32_e32 vcc, s26, v19
	s_nop 1
	v_cndmask_b32_e32 v19, v20, v21, vcc
	s_or_b64 exec, exec, s[14:15]
	v_lshlrev_b16_e32 v56, 6, v0
	v_or_b32_e32 v40, v17, v56
	v_lshlrev_b32_e32 v0, 2, v19
	v_lshl_add_u64 v[20:21], v[14:15], 0, v[0:1]
	v_mul_u32_u24_e32 v0, 0xa00, v40
	v_lshlrev_b32_e32 v0, 2, v0
	v_lshl_add_u64 v[20:21], v[20:21], 0, v[0:1]
	v_add_co_u32_e32 v40, vcc, 0x5000, v20
	s_nop 1
	v_addc_co_u32_e32 v41, vcc, 0, v21, vcc
	v_add_co_u32_e32 v42, vcc, 0xa000, v20
	s_nop 1
	v_addc_co_u32_e32 v43, vcc, 0, v21, vcc
	v_add_co_u32_e32 v44, vcc, 0xf000, v20
	s_nop 1
	v_addc_co_u32_e32 v45, vcc, 0, v21, vcc
	v_add_co_u32_e32 v46, vcc, 0x14000, v20
	s_nop 1
	v_addc_co_u32_e32 v47, vcc, 0, v21, vcc
	v_add_co_u32_e32 v48, vcc, 0x19000, v20
	s_nop 1
	v_addc_co_u32_e32 v49, vcc, 0, v21, vcc
	v_add_co_u32_e32 v50, vcc, 0x1e000, v20
	s_nop 1
	v_addc_co_u32_e32 v51, vcc, 0, v21, vcc
	v_add_co_u32_e32 v52, vcc, 0x23000, v20
	s_nop 1
	v_addc_co_u32_e32 v53, vcc, 0, v21, vcc
	global_load_dword v0, v[20:21], off nt
	global_load_dword v19, v[40:41], off nt
	global_load_dword v57, v[42:43], off nt
	global_load_dword v58, v[44:45], off nt
	global_load_dword v59, v[46:47], off nt
	global_load_dword v60, v[48:49], off nt
	global_load_dword v61, v[50:51], off nt
	global_load_dword v62, v[52:53], off nt
	v_add_co_u32_e32 v40, vcc, 0x28000, v20
	s_nop 1
	v_addc_co_u32_e32 v41, vcc, 0, v21, vcc
	v_add_co_u32_e32 v42, vcc, 0x2d000, v20
	s_nop 1
	v_addc_co_u32_e32 v43, vcc, 0, v21, vcc
	v_add_co_u32_e32 v44, vcc, 0x32000, v20
	s_nop 1
	v_addc_co_u32_e32 v45, vcc, 0, v21, vcc
	v_add_co_u32_e32 v46, vcc, 0x37000, v20
	s_nop 1
	v_addc_co_u32_e32 v47, vcc, 0, v21, vcc
	v_add_co_u32_e32 v48, vcc, 0x3c000, v20
	s_nop 1
	v_addc_co_u32_e32 v49, vcc, 0, v21, vcc
	v_add_co_u32_e32 v50, vcc, 0x41000, v20
	s_nop 1
	v_addc_co_u32_e32 v51, vcc, 0, v21, vcc
	v_add_co_u32_e32 v52, vcc, 0x46000, v20
	s_nop 1
	v_addc_co_u32_e32 v53, vcc, 0, v21, vcc
	v_add_co_u32_e32 v54, vcc, 0x4b000, v20
	s_nop 1
	v_addc_co_u32_e32 v55, vcc, 0, v21, vcc
	global_load_dword v63, v[40:41], off nt
	global_load_dword v64, v[42:43], off nt
	global_load_dword v65, v[44:45], off nt
	global_load_dword v66, v[46:47], off nt
	global_load_dword v67, v[48:49], off nt
	global_load_dword v68, v[50:51], off nt
	global_load_dword v69, v[52:53], off nt
	global_load_dword v70, v[54:55], off nt
	v_add_co_u32_e32 v40, vcc, 0x50000, v20
	s_nop 1
	v_addc_co_u32_e32 v41, vcc, 0, v21, vcc
	v_add_co_u32_e32 v42, vcc, 0x55000, v20
	s_nop 1
	v_addc_co_u32_e32 v43, vcc, 0, v21, vcc
	v_add_co_u32_e32 v44, vcc, 0x5a000, v20
	s_nop 1
	v_addc_co_u32_e32 v45, vcc, 0, v21, vcc
	v_add_co_u32_e32 v46, vcc, 0x5f000, v20
	s_nop 1
	v_addc_co_u32_e32 v47, vcc, 0, v21, vcc
	v_add_co_u32_e32 v48, vcc, 0x64000, v20
	s_nop 1
	v_addc_co_u32_e32 v49, vcc, 0, v21, vcc
	v_add_co_u32_e32 v50, vcc, 0x69000, v20
	s_nop 1
	v_addc_co_u32_e32 v51, vcc, 0, v21, vcc
	v_add_co_u32_e32 v52, vcc, 0x6e000, v20
	s_nop 1
	v_addc_co_u32_e32 v53, vcc, 0, v21, vcc
	v_add_co_u32_e32 v54, vcc, 0x73000, v20
	s_nop 1
	v_addc_co_u32_e32 v55, vcc, 0, v21, vcc
	global_load_dword v71, v[40:41], off nt
	global_load_dword v72, v[42:43], off nt
	global_load_dword v73, v[44:45], off nt
	global_load_dword v74, v[46:47], off nt
	global_load_dword v75, v[48:49], off nt
	global_load_dword v76, v[50:51], off nt
	global_load_dword v77, v[52:53], off nt
	s_nop 0
	global_load_dword v54, v[54:55], off nt
	v_add_co_u32_e32 v40, vcc, 0x78000, v20
	s_nop 1
	v_addc_co_u32_e32 v41, vcc, 0, v21, vcc
	v_add_co_u32_e32 v42, vcc, 0x7d000, v20
	s_nop 1
	v_addc_co_u32_e32 v43, vcc, 0, v21, vcc
	v_add_co_u32_e32 v44, vcc, 0x82000, v20
	s_nop 1
	v_addc_co_u32_e32 v45, vcc, 0, v21, vcc
	v_add_co_u32_e32 v46, vcc, 0x87000, v20
	s_nop 1
	v_addc_co_u32_e32 v47, vcc, 0, v21, vcc
	v_add_co_u32_e32 v48, vcc, 0x8c000, v20
	s_nop 1
	v_addc_co_u32_e32 v49, vcc, 0, v21, vcc
	v_add_co_u32_e32 v50, vcc, 0x91000, v20
	s_nop 1
	v_addc_co_u32_e32 v51, vcc, 0, v21, vcc
	v_add_co_u32_e32 v52, vcc, 0x96000, v20
	s_nop 1
	v_addc_co_u32_e32 v53, vcc, 0, v21, vcc
	v_add_co_u32_e32 v20, vcc, 0x9b000, v20
	s_nop 1
	v_addc_co_u32_e32 v21, vcc, 0, v21, vcc
	global_load_dword v40, v[40:41], off nt
	s_nop 0
	global_load_dword v41, v[42:43], off nt
	s_nop 0
	global_load_dword v42, v[44:45], off nt
	global_load_dword v43, v[46:47], off nt
	s_nop 0
	global_load_dword v44, v[48:49], off nt
	global_load_dword v45, v[50:51], off nt
	global_load_dword v46, v[52:53], off nt
	s_nop 0
	global_load_dword v20, v[20:21], off nt
	s_waitcnt vmcnt(30)
; #define LAS __attribute__((address_space(3)))
; __device__ __forceinline__ unsigned cvt_pk_bf16(float lo, float hi) { unsigned r; asm volatile("v_cvt_pk_bf16_f32 %0, %1, %2" : "=v"(r) : "v"(lo), "v"(hi)); return r; }
; #define ST16(grp, p, v) do { if ((NTG >> (grp)) & 1) NT16(p, v); else PL16(p, v); } while (0)
; __device__ __forceinline__ void transpose_item(const float* W, int K, int N, bf16_t* WT, int n0src, int n0dst, int k0, LAS float* scr, int lane) {
;     ...
;     for (int i = 0; i < 32; ++i) { const int kk = 2 * i + (lane >> 5); scr[kk * 33 + (lane & 31)] = v[i]; }
;     asm volatile("s_waitcnt lgkmcnt(0)" ::: "memory");
;     const int c = lane & 7;
; #pragma unroll
;     for (int j = 0; j < 4; ++j) { const int n = (lane >> 3) + 8 * j; const LAS float* s = scr + (8 * c) * 33 + n;
;         u32x4 o; o.x = cvt_pk_bf16(s[0 * 33], s[1 * 33]); o.y = cvt_pk_bf16(s[2 * 33], s[3 * 33]); o.z = cvt_pk_bf16(s[4 * 33], s[5 * 33]); o.w = cvt_pk_bf16(s[6 * 33], s[7 * 33]);
;         ST16(6, WT + (size_t)(n0dst + n) * K + k0 + 8 * c, o); }
;     asm volatile("s_waitcnt lgkmcnt(0)" ::: "memory");
; }
	ds_write2_b32 v22, v0, v19 offset1:66
	s_waitcnt vmcnt(28)
	ds_write2_b32 v22, v57, v58 offset0:132 offset1:198
	s_waitcnt vmcnt(26)
	ds_write2_b32 v30, v59, v60 offset0:8 offset1:74
	s_waitcnt vmcnt(24)
	ds_write2_b32 v30, v61, v62 offset0:140 offset1:206
	s_waitcnt vmcnt(22)
	ds_write2_b32 v31, v63, v64 offset0:16 offset1:82
	s_waitcnt vmcnt(20)
	ds_write2_b32 v31, v65, v66 offset0:148 offset1:214
	s_waitcnt vmcnt(18)
	ds_write2_b32 v32, v67, v68 offset0:24 offset1:90
	s_waitcnt vmcnt(16)
	ds_write2_b32 v32, v69, v70 offset0:156 offset1:222
	s_waitcnt vmcnt(14)
	ds_write2_b32 v33, v71, v72 offset0:32 offset1:98
	s_waitcnt vmcnt(12)
	ds_write2_b32 v33, v73, v74 offset0:164 offset1:230
	s_waitcnt vmcnt(10)
	ds_write2_b32 v34, v75, v76 offset0:40 offset1:106
	s_waitcnt vmcnt(8)
	ds_write2_b32 v34, v77, v54 offset0:172 offset1:238
	s_waitcnt vmcnt(6)
	ds_write2_b32 v35, v40, v41 offset0:48 offset1:114
	s_waitcnt vmcnt(4)
	ds_write2_b32 v35, v42, v43 offset0:180 offset1:246
	s_waitcnt vmcnt(2)
	ds_write2_b32 v36, v44, v45 offset0:56 offset1:122
	s_waitcnt vmcnt(0)
	ds_write2_b32 v36, v46, v20 offset0:188 offset1:254
	s_waitcnt lgkmcnt(0)
	ds_read2_b32 v[20:21], v24 offset1:33
	s_waitcnt lgkmcnt(0)
	v_cvt_pk_bf16_f32 v40, v20, v21
	ds_read2_b32 v[20:21], v24 offset0:66 offset1:99
	v_lshlrev_b32_e32 v0, 1, v56
	s_waitcnt lgkmcnt(0)
	v_cvt_pk_bf16_f32 v41, v20, v21
	ds_read2_b32 v[20:21], v24 offset0:132 offset1:165
	v_lshl_add_u64 v[44:45], v[8:9], 0, v[0:1]
	v_or_b32_e32 v0, v23, v18
	s_waitcnt lgkmcnt(0)
	v_cvt_pk_bf16_f32 v42, v20, v21
	ds_read2_b32 v[20:21], v24 offset0:198 offset1:231
	v_lshlrev_b32_e32 v0, 11, v0
	s_waitcnt lgkmcnt(0)
	v_cvt_pk_bf16_f32 v43, v20, v21
	ds_read2_b32 v[20:21], v24 offset0:8 offset1:41
	v_lshl_add_u64 v[46:47], v[44:45], 0, v[0:1]
	global_store_dwordx4 v[46:47], v[40:43], off
	v_or_b32_e32 v0, v25, v18
	v_lshlrev_b32_e32 v0, 11, v0
	s_waitcnt lgkmcnt(0)
	v_cvt_pk_bf16_f32 v40, v20, v21
	ds_read2_b32 v[20:21], v24 offset0:74 offset1:107
	s_waitcnt lgkmcnt(0)
	v_cvt_pk_bf16_f32 v41, v20, v21
	ds_read2_b32 v[20:21], v24 offset0:140 offset1:173
	s_waitcnt lgkmcnt(0)
	v_cvt_pk_bf16_f32 v42, v20, v21
	ds_read2_b32 v[20:21], v24 offset0:206 offset1:239
	s_waitcnt lgkmcnt(0)
	v_cvt_pk_bf16_f32 v43, v20, v21
	ds_read2_b32 v[20:21], v24 offset0:16 offset1:49
	v_lshl_add_u64 v[46:47], v[44:45], 0, v[0:1]
	global_store_dwordx4 v[46:47], v[40:43], off
	v_or_b32_e32 v0, v26, v18
	v_lshlrev_b32_e32 v0, 11, v0
	s_waitcnt lgkmcnt(0)
	v_cvt_pk_bf16_f32 v40, v20, v21
	ds_read2_b32 v[20:21], v24 offset0:82 offset1:115
	s_waitcnt lgkmcnt(0)
	v_cvt_pk_bf16_f32 v41, v20, v21
	ds_read2_b32 v[20:21], v24 offset0:148 offset1:181
	s_waitcnt lgkmcnt(0)
	v_cvt_pk_bf16_f32 v42, v20, v21
	ds_read2_b32 v[20:21], v24 offset0:214 offset1:247
	s_waitcnt lgkmcnt(0)
	v_cvt_pk_bf16_f32 v43, v20, v21
	ds_read2_b32 v[20:21], v24 offset0:24 offset1:57
	v_lshl_add_u64 v[46:47], v[44:45], 0, v[0:1]
	v_or_b32_e32 v0, v27, v18
	global_store_dwordx4 v[46:47], v[40:43], off
	v_lshlrev_b32_e32 v0, 11, v0
	v_lshl_add_u64 v[18:19], v[44:45], 0, v[0:1]
	s_waitcnt lgkmcnt(0)
	v_cvt_pk_bf16_f32 v40, v20, v21
	ds_read2_b32 v[20:21], v24 offset0:90 offset1:123
	s_waitcnt lgkmcnt(0)
	v_cvt_pk_bf16_f32 v41, v20, v21
	ds_read2_b32 v[20:21], v24 offset0:156 offset1:189
	s_waitcnt lgkmcnt(0)
	v_cvt_pk_bf16_f32 v42, v20, v21
	ds_read2_b32 v[20:21], v24 offset0:222 offset1:255
	s_waitcnt lgkmcnt(0)
	v_cvt_pk_bf16_f32 v43, v20, v21
	global_store_dwordx4 v[18:19], v[40:43], off
	s_waitcnt lgkmcnt(0)

; #define LAS __attribute__((address_space(3)))
; __device__ __forceinline__ void transpose_item(const float* W, int K, int N, bf16_t* WT, int n0src, int n0dst, int k0, LAS float* scr, int lane) {
;     float v[32];
; #pragma unroll
;     for (int i = 0; i < 32; ++i) { const int kk = 2 * i + (lane >> 5); v[i] = W[(size_t)(k0 + kk) * N + n0src + (lane & 31)]; }
; #pragma unroll
;     for (int i = 0; i < 32; ++i) { const int kk = 2 * i + (lane >> 5); scr[kk * 33 + (lane & 31)] = v[i]; }
; __device__ __forceinline__ void prologue(const Params& p, LAS unsigned char* lds) {
;     ...
;             if (r < 4 * I_W2) { const int mi = r / I_W2; r -= mi * I_W2; const int kb = r / 32, nb = r % 32;
;                 transpose_item(p.in[I_FFNWOUT] + (size_t)mi * DFF * D, DFF, D, (bf16_t*)(ws + WS_W2T + mi * SZ_W2T), nb * 32, nb * 32, kb * 64, scr, lane); continue; }
.LBB0_44:
	s_andn2_saveexec_b64 s[10:11], s[10:11]
	s_cbranch_execz .LBB0_46
	v_add_u32_e32 v0, 0xffffd400, v39
	v_mul_u32_u24_e32 v0, 0xba2f, v0
	v_lshrrev_b32_e32 v21, 26, v0
	v_mul_u32_u24_e32 v0, 0xfa80, v21
	v_add_u32_e32 v0, v0, v39
	v_add_u16_e32 v0, 0xd400, v0
	v_ashrrev_i16_e32 v18, 15, v0
	v_lshrrev_b16_e32 v18, 11, v18
	v_add_u16_e32 v18, v0, v18
	v_readlane_b32 s44, v253, 0
	v_ashrrev_i16_e32 v20, 5, v18
	v_and_b32_e32 v18, 0xffffffe0, v18
	v_readlane_b32 s45, v253, 1
	v_sub_u16_e32 v0, v0, v18
	v_lshlrev_b32_sdwa v20, v38, sext(v20) dst_sel:DWORD dst_unused:UNUSED_PAD src0_sel:DWORD src1_sel:WORD_0
	v_mov_b64_e32 v[18:19], s[44:45]
	v_mad_u64_u32 v[40:41], s[12:13], v21, s33, v[18:19]
	v_lshlrev_b32_sdwa v18, v37, sext(v0) dst_sel:DWORD dst_unused:UNUSED_PAD src0_sel:DWORD src1_sel:WORD_0
	v_or_b32_e32 v42, v20, v17
	v_ashrrev_i32_e32 v19, 31, v18
	v_or_b32_e32 v46, 2, v42
	v_or_b32_e32 v48, 4, v42
	v_or_b32_e32 v50, 6, v42
	v_or_b32_e32 v52, 8, v42
	v_or_b32_e32 v54, 10, v42
	v_or_b32_e32 v56, 12, v42
	v_or_b32_e32 v58, 14, v42
	v_lshl_add_u64 v[40:41], v[18:19], 2, v[40:41]
	v_lshlrev_b32_e32 v0, 2, v16
	v_ashrrev_i32_e32 v43, 31, v42
	v_ashrrev_i32_e32 v47, 31, v46
	v_ashrrev_i32_e32 v49, 31, v48
	v_ashrrev_i32_e32 v51, 31, v50
	v_ashrrev_i32_e32 v53, 31, v52
	v_ashrrev_i32_e32 v55, 31, v54
	v_ashrrev_i32_e32 v57, 31, v56
	v_ashrrev_i32_e32 v59, 31, v58
	v_lshl_add_u64 v[40:41], v[40:41], 0, v[0:1]
	v_lshlrev_b64 v[44:45], 12, v[42:43]
	v_lshlrev_b64 v[46:47], 12, v[46:47]
	v_lshlrev_b64 v[48:49], 12, v[48:49]
	v_lshlrev_b64 v[50:51], 12, v[50:51]
	v_lshlrev_b64 v[52:53], 12, v[52:53]
	v_lshlrev_b64 v[54:55], 12, v[54:55]
	v_lshlrev_b64 v[56:57], 12, v[56:57]
	v_lshlrev_b64 v[58:59], 12, v[58:59]
	v_lshl_add_u64 v[44:45], v[40:41], 0, v[44:45]
	v_lshl_add_u64 v[46:47], v[40:41], 0, v[46:47]
	v_lshl_add_u64 v[48:49], v[40:41], 0, v[48:49]
	v_lshl_add_u64 v[50:51], v[40:41], 0, v[50:51]
	v_lshl_add_u64 v[52:53], v[40:41], 0, v[52:53]
	v_lshl_add_u64 v[54:55], v[40:41], 0, v[54:55]
	v_lshl_add_u64 v[56:57], v[40:41], 0, v[56:57]
	v_lshl_add_u64 v[58:59], v[40:41], 0, v[58:59]
	global_load_dword v0, v[44:45], off nt
	global_load_dword v19, v[46:47], off nt
	global_load_dword v60, v[48:49], off nt
	global_load_dword v61, v[50:51], off nt
	global_load_dword v62, v[52:53], off nt
	global_load_dword v63, v[54:55], off nt
	global_load_dword v64, v[56:57], off nt
	global_load_dword v65, v[58:59], off nt
	v_or_b32_e32 v44, 16, v42
	v_or_b32_e32 v46, 18, v42
	v_or_b32_e32 v48, 20, v42
	v_or_b32_e32 v50, 22, v42
	v_or_b32_e32 v52, 24, v42
	v_or_b32_e32 v54, 26, v42
	v_or_b32_e32 v56, 28, v42
	v_or_b32_e32 v58, 30, v42
	v_ashrrev_i32_e32 v45, 31, v44
	v_ashrrev_i32_e32 v47, 31, v46
	v_ashrrev_i32_e32 v49, 31, v48
	v_ashrrev_i32_e32 v51, 31, v50
	v_ashrrev_i32_e32 v53, 31, v52
	v_ashrrev_i32_e32 v55, 31, v54
	v_ashrrev_i32_e32 v57, 31, v56
	v_ashrrev_i32_e32 v59, 31, v58
	v_lshlrev_b64 v[44:45], 12, v[44:45]
	v_lshlrev_b64 v[46:47], 12, v[46:47]
	v_lshlrev_b64 v[48:49], 12, v[48:49]
	v_lshlrev_b64 v[50:51], 12, v[50:51]
	v_lshlrev_b64 v[52:53], 12, v[52:53]
	v_lshlrev_b64 v[54:55], 12, v[54:55]
	v_lshlrev_b64 v[56:57], 12, v[56:57]
	v_lshlrev_b64 v[58:59], 12, v[58:59]
	v_lshl_add_u64 v[44:45], v[40:41], 0, v[44:45]
	v_lshl_add_u64 v[46:47], v[40:41], 0, v[46:47]
	v_lshl_add_u64 v[48:49], v[40:41], 0, v[48:49]
	v_lshl_add_u64 v[50:51], v[40:41], 0, v[50:51]
	v_lshl_add_u64 v[52:53], v[40:41], 0, v[52:53]
	v_lshl_add_u64 v[54:55], v[40:41], 0, v[54:55]
	v_lshl_add_u64 v[56:57], v[40:41], 0, v[56:57]
	v_lshl_add_u64 v[58:59], v[40:41], 0, v[58:59]
	global_load_dword v66, v[44:45], off nt
	global_load_dword v67, v[46:47], off nt
	global_load_dword v68, v[48:49], off nt
	global_load_dword v69, v[50:51], off nt
	global_load_dword v70, v[52:53], off nt
	global_load_dword v71, v[54:55], off nt
	global_load_dword v72, v[56:57], off nt
	global_load_dword v73, v[58:59], off nt
	v_or_b32_e32 v44, 32, v42
	v_or_b32_e32 v46, 34, v42
	v_or_b32_e32 v48, 36, v42
	v_or_b32_e32 v50, 38, v42
	v_or_b32_e32 v52, 40, v42
	v_or_b32_e32 v54, 42, v42
	v_or_b32_e32 v56, 44, v42
	v_or_b32_e32 v58, 46, v42
	v_ashrrev_i32_e32 v45, 31, v44
	v_ashrrev_i32_e32 v47, 31, v46
	v_ashrrev_i32_e32 v49, 31, v48
	v_ashrrev_i32_e32 v51, 31, v50
	v_ashrrev_i32_e32 v53, 31, v52
	v_ashrrev_i32_e32 v55, 31, v54
	v_ashrrev_i32_e32 v57, 31, v56
	v_ashrrev_i32_e32 v59, 31, v58
	v_lshlrev_b64 v[44:45], 12, v[44:45]
	v_lshlrev_b64 v[46:47], 12, v[46:47]
	v_lshlrev_b64 v[48:49], 12, v[48:49]
	v_lshlrev_b64 v[50:51], 12, v[50:51]
	v_lshlrev_b64 v[52:53], 12, v[52:53]
	v_lshlrev_b64 v[54:55], 12, v[54:55]
	v_lshlrev_b64 v[56:57], 12, v[56:57]
	v_lshlrev_b64 v[58:59], 12, v[58:59]
	v_lshl_add_u64 v[44:45], v[40:41], 0, v[44:45]
	v_lshl_add_u64 v[46:47], v[40:41], 0, v[46:47]
	v_lshl_add_u64 v[48:49], v[40:41], 0, v[48:49]
	v_lshl_add_u64 v[50:51], v[40:41], 0, v[50:51]
	v_lshl_add_u64 v[52:53], v[40:41], 0, v[52:53]
	v_lshl_add_u64 v[54:55], v[40:41], 0, v[54:55]
	v_lshl_add_u64 v[56:57], v[40:41], 0, v[56:57]
	v_lshl_add_u64 v[58:59], v[40:41], 0, v[58:59]
	global_load_dword v74, v[44:45], off nt
	global_load_dword v75, v[46:47], off nt
	global_load_dword v76, v[48:49], off nt
	global_load_dword v77, v[50:51], off nt
	global_load_dword v78, v[52:53], off nt
	global_load_dword v79, v[54:55], off nt
	global_load_dword v80, v[56:57], off nt
	s_nop 0
	global_load_dword v58, v[58:59], off nt
	v_or_b32_e32 v44, 48, v42
	v_or_b32_e32 v46, 50, v42
	v_or_b32_e32 v48, 52, v42
	v_or_b32_e32 v50, 54, v42
	v_or_b32_e32 v52, 56, v42
	v_or_b32_e32 v54, 58, v42
	v_or_b32_e32 v56, 60, v42
	v_or_b32_e32 v42, 62, v42
	v_ashrrev_i32_e32 v45, 31, v44
	v_ashrrev_i32_e32 v47, 31, v46
	v_ashrrev_i32_e32 v49, 31, v48
	v_ashrrev_i32_e32 v51, 31, v50
	v_ashrrev_i32_e32 v53, 31, v52
	v_ashrrev_i32_e32 v55, 31, v54
	v_ashrrev_i32_e32 v57, 31, v56
	v_ashrrev_i32_e32 v43, 31, v42
	v_lshlrev_b64 v[44:45], 12, v[44:45]
	v_lshlrev_b64 v[46:47], 12, v[46:47]
	v_lshlrev_b64 v[48:49], 12, v[48:49]
	v_lshlrev_b64 v[50:51], 12, v[50:51]
	v_lshlrev_b64 v[52:53], 12, v[52:53]
	v_lshlrev_b64 v[54:55], 12, v[54:55]
	v_lshlrev_b64 v[56:57], 12, v[56:57]
	v_lshlrev_b64 v[42:43], 12, v[42:43]
	v_lshl_add_u64 v[44:45], v[40:41], 0, v[44:45]
	v_lshl_add_u64 v[46:47], v[40:41], 0, v[46:47]
	v_lshl_add_u64 v[48:49], v[40:41], 0, v[48:49]
	v_lshl_add_u64 v[50:51], v[40:41], 0, v[50:51]
	v_lshl_add_u64 v[52:53], v[40:41], 0, v[52:53]
	v_lshl_add_u64 v[54:55], v[40:41], 0, v[54:55]
	v_lshl_add_u64 v[56:57], v[40:41], 0, v[56:57]
	v_lshl_add_u64 v[40:41], v[40:41], 0, v[42:43]
	global_load_dword v42, v[44:45], off nt
	global_load_dword v43, v[46:47], off nt
	s_nop 0
	global_load_dword v44, v[48:49], off nt
	global_load_dword v45, v[50:51], off nt
	global_load_dword v46, v[52:53], off nt
	global_load_dword v47, v[54:55], off nt
	s_nop 0
	global_load_dword v48, v[56:57], off nt
	s_nop 0
	global_load_dword v40, v[40:41], off nt
	s_waitcnt vmcnt(30)
; #define LAS __attribute__((address_space(3)))
; __device__ __forceinline__ unsigned cvt_pk_bf16(float lo, float hi) { unsigned r; asm volatile("v_cvt_pk_bf16_f32 %0, %1, %2" : "=v"(r) : "v"(lo), "v"(hi)); return r; }
; #define ST16(grp, p, v) do { if ((NTG >> (grp)) & 1) NT16(p, v); else PL16(p, v); } while (0)
; __device__ __forceinline__ void transpose_item(const float* W, int K, int N, bf16_t* WT, int n0src, int n0dst, int k0, LAS float* scr, int lane) {
;     ...
;     for (int i = 0; i < 32; ++i) { const int kk = 2 * i + (lane >> 5); scr[kk * 33 + (lane & 31)] = v[i]; }
;     asm volatile("s_waitcnt lgkmcnt(0)" ::: "memory");
;     const int c = lane & 7;
; #pragma unroll
;     for (int j = 0; j < 4; ++j) { const int n = (lane >> 3) + 8 * j; const LAS float* s = scr + (8 * c) * 33 + n;
;         u32x4 o; o.x = cvt_pk_bf16(s[0 * 33], s[1 * 33]); o.y = cvt_pk_bf16(s[2 * 33], s[3 * 33]); o.z = cvt_pk_bf16(s[4 * 33], s[5 * 33]); o.w = cvt_pk_bf16(s[6 * 33], s[7 * 33]);
;         ST16(6, WT + (size_t)(n0dst + n) * K + k0 + 8 * c, o); }
;     asm volatile("s_waitcnt lgkmcnt(0)" ::: "memory");
; }
	ds_write2_b32 v22, v0, v19 offset1:66
	s_waitcnt vmcnt(28)
	ds_write2_b32 v22, v60, v61 offset0:132 offset1:198
	s_waitcnt vmcnt(26)
	ds_write2_b32 v30, v62, v63 offset0:8 offset1:74
	s_waitcnt vmcnt(24)
	ds_write2_b32 v30, v64, v65 offset0:140 offset1:206
	s_waitcnt vmcnt(22)
	ds_write2_b32 v31, v66, v67 offset0:16 offset1:82
	s_waitcnt vmcnt(20)
	ds_write2_b32 v31, v68, v69 offset0:148 offset1:214
	s_waitcnt vmcnt(18)
	ds_write2_b32 v32, v70, v71 offset0:24 offset1:90
	s_waitcnt vmcnt(16)
	ds_write2_b32 v32, v72, v73 offset0:156 offset1:222
	s_waitcnt vmcnt(14)
	ds_write2_b32 v33, v74, v75 offset0:32 offset1:98
	s_waitcnt vmcnt(12)
	ds_write2_b32 v33, v76, v77 offset0:164 offset1:230
	s_waitcnt vmcnt(10)
	ds_write2_b32 v34, v78, v79 offset0:40 offset1:106
	s_waitcnt vmcnt(8)
	ds_write2_b32 v34, v80, v58 offset0:172 offset1:238
	s_waitcnt vmcnt(6)
	ds_write2_b32 v35, v42, v43 offset0:48 offset1:114
	s_waitcnt vmcnt(4)
	ds_write2_b32 v35, v44, v45 offset0:180 offset1:246
	s_waitcnt vmcnt(2)
	ds_write2_b32 v36, v46, v47 offset0:56 offset1:122
	s_waitcnt vmcnt(0)
	ds_write2_b32 v36, v48, v40 offset0:188 offset1:254
	s_waitcnt lgkmcnt(0)
	ds_read2_b32 v[40:41], v24 offset1:33
	v_mov_b64_e32 v[44:45], s[2:3]
	s_waitcnt lgkmcnt(0)
	v_cvt_pk_bf16_f32 v40, v40, v41
	ds_read2_b32 v[42:43], v24 offset0:66 offset1:99
	v_mad_u64_u32 v[44:45], s[12:13], v21, s34, v[44:45]
	v_ashrrev_i32_e32 v21, 31, v20
	s_waitcnt lgkmcnt(0)
	v_cvt_pk_bf16_f32 v41, v42, v43
	ds_read2_b32 v[42:43], v24 offset0:132 offset1:165
	v_lshl_add_u64 v[20:21], v[20:21], 1, v[44:45]
	v_lshlrev_b32_e32 v0, 1, v2
	s_waitcnt lgkmcnt(0)
	v_cvt_pk_bf16_f32 v42, v42, v43
	ds_read2_b32 v[46:47], v24 offset0:198 offset1:231
	v_lshl_add_u64 v[20:21], v[20:21], 0, v[0:1]
	v_or_b32_e32 v0, v18, v23
	s_waitcnt lgkmcnt(0)
	v_cvt_pk_bf16_f32 v43, v46, v47
	v_mul_i32_i24_e32 v46, 0xb00, v0
	v_ashrrev_i32_e32 v47, 31, v46
	v_lshl_add_u64 v[46:47], v[46:47], 1, v[20:21]
	v_or_b32_e32 v0, v18, v25
	ds_read2_b32 v[44:45], v24 offset0:8 offset1:41
	global_store_dwordx4 v[46:47], v[40:43], off
	v_mul_i32_i24_e32 v46, 0xb00, v0
	v_ashrrev_i32_e32 v47, 31, v46
	s_waitcnt lgkmcnt(0)
	v_cvt_pk_bf16_f32 v40, v44, v45
	ds_read2_b32 v[42:43], v24 offset0:74 offset1:107
	s_waitcnt lgkmcnt(0)
	v_cvt_pk_bf16_f32 v41, v42, v43
	ds_read2_b32 v[42:43], v24 offset0:140 offset1:173
	s_waitcnt lgkmcnt(0)
	v_cvt_pk_bf16_f32 v42, v42, v43
	ds_read2_b32 v[44:45], v24 offset0:206 offset1:239
	s_waitcnt lgkmcnt(0)
	v_cvt_pk_bf16_f32 v43, v44, v45
	v_lshl_add_u64 v[46:47], v[46:47], 1, v[20:21]
	v_or_b32_e32 v0, v18, v26
	ds_read2_b32 v[44:45], v24 offset0:16 offset1:49
	global_store_dwordx4 v[46:47], v[40:43], off
	v_mul_i32_i24_e32 v46, 0xb00, v0
	v_ashrrev_i32_e32 v47, 31, v46
	s_waitcnt lgkmcnt(0)
	v_cvt_pk_bf16_f32 v40, v44, v45
	ds_read2_b32 v[42:43], v24 offset0:82 offset1:115
	s_waitcnt lgkmcnt(0)
	v_cvt_pk_bf16_f32 v41, v42, v43
	ds_read2_b32 v[42:43], v24 offset0:148 offset1:181
	v_or_b32_e32 v0, v18, v27
	s_waitcnt lgkmcnt(0)
	v_cvt_pk_bf16_f32 v42, v42, v43
	ds_read2_b32 v[44:45], v24 offset0:214 offset1:247
	s_waitcnt lgkmcnt(0)
	v_cvt_pk_bf16_f32 v43, v44, v45
	v_lshl_add_u64 v[46:47], v[46:47], 1, v[20:21]
	v_mul_i32_i24_e32 v18, 0xb00, v0
	ds_read2_b32 v[44:45], v24 offset0:24 offset1:57
	global_store_dwordx4 v[46:47], v[40:43], off
	v_ashrrev_i32_e32 v19, 31, v18
	v_lshl_add_u64 v[18:19], v[18:19], 1, v[20:21]
	s_waitcnt lgkmcnt(0)
	v_cvt_pk_bf16_f32 v40, v44, v45
	ds_read2_b32 v[42:43], v24 offset0:90 offset1:123
	s_waitcnt lgkmcnt(0)
	v_cvt_pk_bf16_f32 v41, v42, v43
	ds_read2_b32 v[42:43], v24 offset0:156 offset1:189
	s_waitcnt lgkmcnt(0)
	v_cvt_pk_bf16_f32 v42, v42, v43
	ds_read2_b32 v[44:45], v24 offset0:222 offset1:255
	s_waitcnt lgkmcnt(0)
	v_cvt_pk_bf16_f32 v43, v44, v45
	global_store_dwordx4 v[18:19], v[40:43], off
	s_waitcnt lgkmcnt(0)
	v_readlane_b32 s46, v253, 2
	v_readlane_b32 s47, v253, 3
	v_readlane_b32 s48, v253, 4
	v_readlane_b32 s49, v253, 5
	v_readlane_b32 s50, v253, 6
	v_readlane_b32 s51, v253, 7
	v_readlane_b32 s52, v253, 8
	v_readlane_b32 s53, v253, 9
	v_readlane_b32 s54, v253, 10
	v_readlane_b32 s55, v253, 11
	v_readlane_b32 s56, v253, 12
	v_readlane_b32 s57, v253, 13
	v_readlane_b32 s58, v253, 14
	v_readlane_b32 s59, v253, 15

; #define LAS __attribute__((address_space(3)))
; __device__ __forceinline__ unsigned cvt_pk_bf16(float lo, float hi) { unsigned r; asm volatile("v_cvt_pk_bf16_f32 %0, %1, %2" : "=v"(r) : "v"(lo), "v"(hi)); return r; }
; #define ST16(grp, p, v) do { if ((NTG >> (grp)) & 1) NT16(p, v); else PL16(p, v); } while (0)
; __device__ __forceinline__ void transpose_item(const float* W, int K, int N, bf16_t* WT, int n0src, int n0dst, int k0, LAS float* scr, int lane) {
;     float v[32];
; #pragma unroll
;     for (int i = 0; i < 32; ++i) { const int kk = 2 * i + (lane >> 5); v[i] = W[(size_t)(k0 + kk) * N + n0src + (lane & 31)]; }
; #pragma unroll
;     for (int i = 0; i < 32; ++i) { const int kk = 2 * i + (lane >> 5); scr[kk * 33 + (lane & 31)] = v[i]; }
;     asm volatile("s_waitcnt lgkmcnt(0)" ::: "memory");
;     const int c = lane & 7;
; #pragma unroll
;     for (int j = 0; j < 4; ++j) { const int n = (lane >> 3) + 8 * j; const LAS float* s = scr + (8 * c) * 33 + n;
;         u32x4 o; o.x = cvt_pk_bf16(s[0 * 33], s[1 * 33]); o.y = cvt_pk_bf16(s[2 * 33], s[3 * 33]); o.z = cvt_pk_bf16(s[4 * 33], s[5 * 33]); o.w = cvt_pk_bf16(s[6 * 33], s[7 * 33]);
;         ST16(6, WT + (size_t)(n0dst + n) * K + k0 + 8 * c, o); }
;     asm volatile("s_waitcnt lgkmcnt(0)" ::: "memory");
; }
; __device__ __forceinline__ void prologue(const Params& p, LAS unsigned char* lds) {
;     ...
;             if (r < 4 * I_W1) { const int mi = r / I_W1; r -= mi * I_W1; const int kb = r / 176, nb = r % 176;
;                 transpose_item(p.in[I_FFNWIN] + (size_t)mi * D * NFF1, D, NFF1, (bf16_t*)(ws + WS_W1T + mi * SZ_W1T), paired_src(nb * 32, DFF), nb * 32, kb * 64, scr, lane); continue; }
.LBB0_47:
	s_andn2_saveexec_b64 s[8:9], s[8:9]
	s_cbranch_execz .LBB0_30
	v_mul_hi_i32 v0, v39, s35
	v_lshrrev_b32_e32 v18, 31, v0
	v_ashrrev_i32_e32 v0, 9, v0
	v_add_u32_e32 v41, v0, v18
	v_mul_i32_i24_e32 v0, 0xfffff500, v41
	v_add_u32_e32 v0, v0, v39
	v_mul_hi_i32 v18, v0, s35
	v_lshrrev_b32_e32 v19, 31, v18
	v_ashrrev_i32_e32 v18, 5, v18
	v_add_u32_e32 v21, v18, v19
	v_mul_lo_u32 v18, v21, s36
	v_sub_u32_e32 v0, v0, v18
	v_lshlrev_b32_e32 v56, 5, v0
	v_lshlrev_b32_e32 v0, 4, v0
	v_and_b32_e32 v20, 0xe0, v56
	v_and_b32_e32 v0, 0xffffff80, v0
	v_or_b32_e32 v40, v0, v20
	v_add3_u32 v0, v20, v0, s38
	v_cmp_gt_u32_e32 vcc, s26, v20
	v_mov_b64_e32 v[18:19], s[30:31]
	v_mad_i64_i32 v[18:19], s[10:11], v41, s37, v[18:19]
	v_cndmask_b32_e32 v20, v0, v40, vcc
	v_lshlrev_b32_e32 v40, 6, v21
	v_ashrrev_i32_e32 v21, 31, v20
	v_or_b32_e32 v57, v40, v17
	v_lshl_add_u64 v[18:19], v[20:21], 2, v[18:19]
	v_lshlrev_b32_e32 v0, 2, v16
	v_lshl_add_u64 v[18:19], v[18:19], 0, v[0:1]
	v_or_b32_e32 v0, 2, v57
	v_mad_i64_i32 v[42:43], s[10:11], v0, s39, v[18:19]
	v_or_b32_e32 v0, 4, v57
	v_mad_i64_i32 v[44:45], s[10:11], v0, s39, v[18:19]
	v_or_b32_e32 v0, 6, v57
	v_mad_i64_i32 v[46:47], s[10:11], v0, s39, v[18:19]
	v_or_b32_e32 v0, 8, v57
	v_mad_i64_i32 v[48:49], s[10:11], v0, s39, v[18:19]
	v_or_b32_e32 v0, 10, v57
	v_mad_i64_i32 v[50:51], s[10:11], v0, s39, v[18:19]
	v_or_b32_e32 v0, 12, v57
	v_mad_i64_i32 v[52:53], s[10:11], v0, s39, v[18:19]
	v_or_b32_e32 v0, 14, v57
	v_mad_i64_i32 v[20:21], s[10:11], v57, s39, v[18:19]
	v_mad_i64_i32 v[54:55], s[10:11], v0, s39, v[18:19]
	global_load_dword v0, v[20:21], off nt
	global_load_dword v58, v[42:43], off nt
	global_load_dword v59, v[44:45], off nt
	global_load_dword v60, v[46:47], off nt
	global_load_dword v61, v[48:49], off nt
	global_load_dword v62, v[50:51], off nt
	global_load_dword v63, v[52:53], off nt
	global_load_dword v64, v[54:55], off nt
	v_or_b32_e32 v20, 16, v57
	v_or_b32_e32 v42, 18, v57
	v_or_b32_e32 v44, 20, v57
	v_or_b32_e32 v46, 22, v57
	v_or_b32_e32 v48, 24, v57
	v_or_b32_e32 v50, 26, v57
	v_or_b32_e32 v52, 28, v57
	v_or_b32_e32 v54, 30, v57
	v_mad_i64_i32 v[20:21], s[10:11], v20, s39, v[18:19]
	v_mad_i64_i32 v[42:43], s[10:11], v42, s39, v[18:19]
	v_mad_i64_i32 v[44:45], s[10:11], v44, s39, v[18:19]
	v_mad_i64_i32 v[46:47], s[10:11], v46, s39, v[18:19]
	v_mad_i64_i32 v[48:49], s[10:11], v48, s39, v[18:19]
	v_mad_i64_i32 v[50:51], s[10:11], v50, s39, v[18:19]
	v_mad_i64_i32 v[52:53], s[10:11], v52, s39, v[18:19]
	v_mad_i64_i32 v[54:55], s[10:11], v54, s39, v[18:19]
	global_load_dword v65, v[20:21], off nt
	global_load_dword v66, v[42:43], off nt
	global_load_dword v67, v[44:45], off nt
	global_load_dword v68, v[46:47], off nt
	global_load_dword v69, v[48:49], off nt
	global_load_dword v70, v[50:51], off nt
	global_load_dword v71, v[52:53], off nt
	global_load_dword v72, v[54:55], off nt
	v_or_b32_e32 v20, 32, v57
	v_or_b32_e32 v42, 34, v57
	v_or_b32_e32 v44, 36, v57
	v_or_b32_e32 v46, 38, v57
	v_or_b32_e32 v48, 40, v57
	v_or_b32_e32 v50, 42, v57
	v_or_b32_e32 v52, 44, v57
	v_or_b32_e32 v54, 46, v57
	v_mad_i64_i32 v[20:21], s[10:11], v20, s39, v[18:19]
	v_mad_i64_i32 v[42:43], s[10:11], v42, s39, v[18:19]
	v_mad_i64_i32 v[44:45], s[10:11], v44, s39, v[18:19]
	v_mad_i64_i32 v[46:47], s[10:11], v46, s39, v[18:19]
	v_mad_i64_i32 v[48:49], s[10:11], v48, s39, v[18:19]
	v_mad_i64_i32 v[50:51], s[10:11], v50, s39, v[18:19]
	v_mad_i64_i32 v[52:53], s[10:11], v52, s39, v[18:19]
	v_mad_i64_i32 v[54:55], s[10:11], v54, s39, v[18:19]
	global_load_dword v73, v[20:21], off nt
	global_load_dword v74, v[42:43], off nt
	global_load_dword v75, v[44:45], off nt
	global_load_dword v76, v[46:47], off nt
	global_load_dword v77, v[48:49], off nt
	global_load_dword v78, v[50:51], off nt
	global_load_dword v79, v[52:53], off nt
	s_nop 0
	global_load_dword v54, v[54:55], off nt
	v_or_b32_e32 v20, 48, v57
	v_or_b32_e32 v42, 50, v57
	v_or_b32_e32 v44, 52, v57
	v_or_b32_e32 v46, 54, v57
	v_or_b32_e32 v48, 56, v57
	v_or_b32_e32 v50, 58, v57
	v_or_b32_e32 v52, 60, v57
	v_or_b32_e32 v55, 62, v57
	v_mad_i64_i32 v[20:21], s[10:11], v20, s39, v[18:19]
	v_mad_i64_i32 v[42:43], s[10:11], v42, s39, v[18:19]
	v_mad_i64_i32 v[44:45], s[10:11], v44, s39, v[18:19]
	v_mad_i64_i32 v[46:47], s[10:11], v46, s39, v[18:19]
	v_mad_i64_i32 v[48:49], s[10:11], v48, s39, v[18:19]
	v_mad_i64_i32 v[50:51], s[10:11], v50, s39, v[18:19]
	v_mad_i64_i32 v[52:53], s[10:11], v52, s39, v[18:19]
	v_mad_i64_i32 v[18:19], s[10:11], v55, s39, v[18:19]
	global_load_dword v20, v[20:21], off nt
	s_nop 0
	global_load_dword v21, v[42:43], off nt
	s_nop 0
	global_load_dword v42, v[44:45], off nt
	global_load_dword v43, v[46:47], off nt
	s_nop 0
	global_load_dword v44, v[48:49], off nt
	global_load_dword v45, v[50:51], off nt
	global_load_dword v46, v[52:53], off nt
	s_nop 0
	global_load_dword v18, v[18:19], off nt
	s_waitcnt vmcnt(30)
; #define LAS __attribute__((address_space(3)))
; __device__ __forceinline__ unsigned cvt_pk_bf16(float lo, float hi) { unsigned r; asm volatile("v_cvt_pk_bf16_f32 %0, %1, %2" : "=v"(r) : "v"(lo), "v"(hi)); return r; }
; #define ST16(grp, p, v) do { if ((NTG >> (grp)) & 1) NT16(p, v); else PL16(p, v); } while (0)
; __device__ __forceinline__ void transpose_item(const float* W, int K, int N, bf16_t* WT, int n0src, int n0dst, int k0, LAS float* scr, int lane) {
;     ...
;     for (int i = 0; i < 32; ++i) { const int kk = 2 * i + (lane >> 5); scr[kk * 33 + (lane & 31)] = v[i]; }
;     asm volatile("s_waitcnt lgkmcnt(0)" ::: "memory");
;     const int c = lane & 7;
; #pragma unroll
;     for (int j = 0; j < 4; ++j) { const int n = (lane >> 3) + 8 * j; const LAS float* s = scr + (8 * c) * 33 + n;
;         u32x4 o; o.x = cvt_pk_bf16(s[0 * 33], s[1 * 33]); o.y = cvt_pk_bf16(s[2 * 33], s[3 * 33]); o.z = cvt_pk_bf16(s[4 * 33], s[5 * 33]); o.w = cvt_pk_bf16(s[6 * 33], s[7 * 33]);
;         ST16(6, WT + (size_t)(n0dst + n) * K + k0 + 8 * c, o); }
;     asm volatile("s_waitcnt lgkmcnt(0)" ::: "memory");
; }
	ds_write2_b32 v22, v0, v58 offset1:66
	s_waitcnt vmcnt(28)
	ds_write2_b32 v22, v59, v60 offset0:132 offset1:198
	s_waitcnt vmcnt(26)
	ds_write2_b32 v30, v61, v62 offset0:8 offset1:74
	s_waitcnt vmcnt(24)
	ds_write2_b32 v30, v63, v64 offset0:140 offset1:206
	s_waitcnt vmcnt(22)
	ds_write2_b32 v31, v65, v66 offset0:16 offset1:82
	s_waitcnt vmcnt(20)
	ds_write2_b32 v31, v67, v68 offset0:148 offset1:214
	s_waitcnt vmcnt(18)
	ds_write2_b32 v32, v69, v70 offset0:24 offset1:90
	s_waitcnt vmcnt(16)
	ds_write2_b32 v32, v71, v72 offset0:156 offset1:222
	s_waitcnt vmcnt(14)
	ds_write2_b32 v33, v73, v74 offset0:32 offset1:98
	s_waitcnt vmcnt(12)
	ds_write2_b32 v33, v75, v76 offset0:164 offset1:230
	s_waitcnt vmcnt(10)
	ds_write2_b32 v34, v77, v78 offset0:40 offset1:106
	s_waitcnt vmcnt(8)
	ds_write2_b32 v34, v79, v54 offset0:172 offset1:238
	s_waitcnt vmcnt(6)
	ds_write2_b32 v35, v20, v21 offset0:48 offset1:114
	s_waitcnt vmcnt(4)
	ds_write2_b32 v35, v42, v43 offset0:180 offset1:246
	s_waitcnt vmcnt(2)
	ds_write2_b32 v36, v44, v45 offset0:56 offset1:122
	s_waitcnt vmcnt(0)
	ds_write2_b32 v36, v46, v18 offset0:188 offset1:254
	v_mov_b64_e32 v[42:43], s[4:5]
	s_waitcnt lgkmcnt(0)
	v_mad_i64_i32 v[42:43], s[10:11], v41, s33, v[42:43]
	v_ashrrev_i32_e32 v41, 31, v40
	ds_read2_b32 v[18:19], v24 offset1:33
	v_lshl_add_u64 v[40:41], v[40:41], 1, v[42:43]
	v_or_b32_e32 v42, v56, v23
	s_waitcnt lgkmcnt(0)
	v_cvt_pk_bf16_f32 v18, v18, v19
	ds_read2_b32 v[20:21], v24 offset0:66 offset1:99
	v_lshlrev_b32_e32 v0, 1, v2
	v_ashrrev_i32_e32 v43, 31, v42
	s_waitcnt lgkmcnt(0)
	v_cvt_pk_bf16_f32 v19, v20, v21
	ds_read2_b32 v[20:21], v24 offset0:132 offset1:165
	v_lshl_add_u64 v[40:41], v[40:41], 0, v[0:1]
	v_lshlrev_b64 v[42:43], 11, v[42:43]
	s_waitcnt lgkmcnt(0)
	v_cvt_pk_bf16_f32 v20, v20, v21
	ds_read2_b32 v[44:45], v24 offset0:198 offset1:231
	s_waitcnt lgkmcnt(0)
	v_cvt_pk_bf16_f32 v21, v44, v45
	v_lshl_add_u64 v[42:43], v[40:41], 0, v[42:43]
	ds_read2_b32 v[44:45], v24 offset0:8 offset1:41
	global_store_dwordx4 v[42:43], v[18:21], off
	s_waitcnt lgkmcnt(0)
	s_nop 0
	v_cvt_pk_bf16_f32 v18, v44, v45
	ds_read2_b32 v[20:21], v24 offset0:74 offset1:107
	s_waitcnt lgkmcnt(0)
	v_cvt_pk_bf16_f32 v19, v20, v21
	ds_read2_b32 v[20:21], v24 offset0:140 offset1:173
	s_waitcnt lgkmcnt(0)
	v_cvt_pk_bf16_f32 v20, v20, v21
	ds_read2_b32 v[42:43], v24 offset0:206 offset1:239
	s_waitcnt lgkmcnt(0)
	v_cvt_pk_bf16_f32 v21, v42, v43
	v_or_b32_e32 v42, v56, v25
	v_ashrrev_i32_e32 v43, 31, v42
	v_lshlrev_b64 v[42:43], 11, v[42:43]
	v_lshl_add_u64 v[42:43], v[40:41], 0, v[42:43]
	ds_read2_b32 v[44:45], v24 offset0:16 offset1:49
	global_store_dwordx4 v[42:43], v[18:21], off
	s_waitcnt lgkmcnt(0)
	s_nop 0
	v_cvt_pk_bf16_f32 v18, v44, v45
	ds_read2_b32 v[20:21], v24 offset0:82 offset1:115
	s_waitcnt lgkmcnt(0)
	v_cvt_pk_bf16_f32 v19, v20, v21
	ds_read2_b32 v[20:21], v24 offset0:148 offset1:181
	s_waitcnt lgkmcnt(0)
	v_cvt_pk_bf16_f32 v20, v20, v21
	ds_read2_b32 v[42:43], v24 offset0:214 offset1:247
	s_waitcnt lgkmcnt(0)
	v_cvt_pk_bf16_f32 v21, v42, v43
	v_or_b32_e32 v42, v56, v26
	v_ashrrev_i32_e32 v43, 31, v42
	v_lshlrev_b64 v[42:43], 11, v[42:43]
	v_lshl_add_u64 v[42:43], v[40:41], 0, v[42:43]
	ds_read2_b32 v[44:45], v24 offset0:24 offset1:57
	global_store_dwordx4 v[42:43], v[18:21], off
	s_waitcnt lgkmcnt(0)
	s_nop 0
	v_cvt_pk_bf16_f32 v18, v44, v45
	ds_read2_b32 v[20:21], v24 offset0:90 offset1:123
	s_waitcnt lgkmcnt(0)
	v_cvt_pk_bf16_f32 v19, v20, v21
	ds_read2_b32 v[20:21], v24 offset0:156 offset1:189
	s_waitcnt lgkmcnt(0)
	v_cvt_pk_bf16_f32 v20, v20, v21
	ds_read2_b32 v[42:43], v24 offset0:222 offset1:255
	s_waitcnt lgkmcnt(0)
	v_cvt_pk_bf16_f32 v21, v42, v43
	v_or_b32_e32 v42, v56, v27
	v_ashrrev_i32_e32 v43, 31, v42
	v_lshlrev_b64 v[42:43], 11, v[42:43]
	v_lshl_add_u64 v[40:41], v[40:41], 0, v[42:43]
	global_store_dwordx4 v[40:41], v[18:21], off
	s_waitcnt lgkmcnt(0)
	s_branch .LBB0_30

; __device__ __forceinline__ void prenorm_rows(const float* src0, const float* src1, int row_lo, int row_hi, const float* g, const float* scale, float* SS, bf16_t* HB) {
;     ...
;     for (int row = row_lo + gw; row < row_hi; row += 2 * NGW) {
;         const int rowb = row + NGW; const bool hasb = rowb < row_hi; const int rb = hasb ? rowb : row;
;         const float* srca = row < NTOK ? src0 + (size_t)row * D : src1 + (size_t)(row - NTOK) * D;
;         const float* srcb = rb < NTOK ? src0 + (size_t)rb * D : src1 + (size_t)(rb - NTOK) * D;
;         const int mba = row < NTOK ? (row >> 12) : 4, mbb = rb < NTOK ? (rb >> 12) : 4;
;         const f32x4* xa = (const f32x4*)srca + lane; const f32x4* xb = (const f32x4*)srcb + lane;
;         f32x4 va[4], vb[4]; float sa = 0.f, sb = 0.f;
; #pragma unroll
;         for (int j = 0; j < 4; ++j) { va[j] = xa[64 * j]; vb[j] = xb[64 * j]; }
; #pragma unroll
;         for (int j = 0; j < 4; ++j) { sa += (va[j][0] * va[j][0] + va[j][1] * va[j][1]) + (va[j][2] * va[j][2] + va[j][3] * va[j][3]); sb += (vb[j][0] * vb[j][0] + vb[j][1] * vb[j][1]) + (vb[j][2] * vb[j][2] + vb[j][3] * vb[j][3]); }
;         sa = wave_sum(sa); sb = wave_sum(sb);
;         if (lane == 0) { SS[row] = sa; if (hasb) SS[rowb] = sb; }
.LBB0_137:
	v_add_u32_e32 v0, 0xffffc000, v48
	v_ashrrev_i32_e32 v49, 31, v48
	v_cmp_gt_i32_e64 s[0:1], s26, v48
	v_add_u32_e32 v66, s94, v48
	s_nop 0
	v_cndmask_b32_e64 v1, 0, v49, s[0:1]
	v_cndmask_b32_e64 v0, v0, v48, s[0:1]
	v_cndmask_b32_e64 v3, v62, v63, s[0:1]
	v_cndmask_b32_e64 v2, v64, v65, s[0:1]
	v_lshlrev_b64 v[0:1], 12, v[0:1]
	v_lshl_add_u64 v[0:1], v[2:3], 0, v[0:1]
	v_cmp_gt_i32_e64 s[0:1], s19, v66
	v_lshl_add_u64 v[0:1], v[0:1], 0, v[46:47]
	global_load_dwordx4 v[28:31], v[0:1], off nt
	v_cndmask_b32_e64 v50, v48, v66, s[0:1]
	global_load_dwordx4 v[20:23], v[0:1], off offset:1024 nt
	global_load_dwordx4 v[12:15], v[0:1], off offset:2048 nt
	global_load_dwordx4 v[4:7], v[0:1], off offset:3072 nt
	v_add_u32_e32 v0, 0xffffc000, v50
	v_ashrrev_i32_e32 v51, 31, v50
	v_cmp_gt_i32_e64 s[12:13], s26, v50
	s_waitcnt vmcnt(3)
	v_mul_f32_e32 v32, v29, v29
	v_cndmask_b32_e64 v1, 0, v51, s[12:13]
	v_cndmask_b32_e64 v0, v0, v50, s[12:13]
	v_cndmask_b32_e64 v3, v62, v63, s[12:13]
	v_cndmask_b32_e64 v2, v64, v65, s[12:13]
	v_lshlrev_b64 v[0:1], 12, v[0:1]
	v_lshl_add_u64 v[0:1], v[2:3], 0, v[0:1]
	v_lshl_add_u64 v[0:1], v[0:1], 0, v[46:47]
	global_load_dwordx4 v[24:27], v[0:1], off nt
	global_load_dwordx4 v[16:19], v[0:1], off offset:1024 nt
	global_load_dwordx4 v[8:11], v[0:1], off offset:2048 nt
	s_nop 0
	global_load_dwordx4 v[0:3], v[0:1], off offset:3072 nt
	v_mul_f32_e32 v33, v31, v31
	s_waitcnt vmcnt(6)
	v_mul_f32_e32 v34, v21, v21
	v_mul_f32_e32 v35, v23, v23
	s_waitcnt vmcnt(5)
	v_mul_f32_e32 v36, v13, v13
	v_mul_f32_e32 v37, v15, v15
	v_fmac_f32_e32 v32, v28, v28
	v_fmac_f32_e32 v33, v30, v30
	v_fmac_f32_e32 v34, v20, v20
	v_fmac_f32_e32 v35, v22, v22
	s_waitcnt vmcnt(4)
	v_mul_f32_e32 v38, v5, v5
	v_mul_f32_e32 v39, v7, v7
	v_fmac_f32_e32 v36, v12, v12
	v_fmac_f32_e32 v37, v14, v14
	v_add_f32_e32 v32, v32, v33
	v_add_f32_e32 v34, v34, v35
	v_fmac_f32_e32 v38, v4, v4
	v_fmac_f32_e32 v39, v6, v6
	v_add_f32_e32 v36, v36, v37
	v_add_f32_e32 v38, v38, v39
	v_add_f32_e32 v32, v32, v34
	v_add_f32_e32 v32, v32, v36
	v_add_f32_e32 v32, v32, v38
	s_waitcnt vmcnt(3)
	v_mul_f32_e32 v33, v25, v25
	v_mul_f32_e32 v52, v27, v27
	s_waitcnt vmcnt(2)
	v_mul_f32_e32 v35, v17, v17
	v_mul_f32_e32 v53, v19, v19
	s_waitcnt vmcnt(1)
	v_mul_f32_e32 v37, v9, v9
	v_mul_f32_e32 v54, v11, v11
	v_fmac_f32_e32 v33, v24, v24
	v_fmac_f32_e32 v52, v26, v26
	v_fmac_f32_e32 v35, v16, v16
	v_fmac_f32_e32 v53, v18, v18
	s_waitcnt vmcnt(0)
	v_mul_f32_e32 v39, v1, v1
	v_mul_f32_e32 v55, v3, v3
	v_fmac_f32_e32 v37, v8, v8
	v_fmac_f32_e32 v54, v10, v10
	v_add_f32_e32 v33, v33, v52
	v_add_f32_e32 v34, v35, v53
	v_fmac_f32_e32 v39, v0, v0
	v_fmac_f32_e32 v55, v2, v2
	v_add_f32_e32 v35, v37, v54
	v_add_f32_e32 v33, v33, v34
	v_add_f32_e32 v36, v39, v55
	v_add_f32_e32 v33, v33, v35
	v_add_f32_e32 v33, v33, v36
	ds_bpermute_b32 v34, v56, v32
	ds_bpermute_b32 v35, v56, v33
	s_waitcnt lgkmcnt(1)
	v_add_f32_e32 v32, v32, v34
	s_waitcnt lgkmcnt(0)
	v_add_f32_e32 v33, v33, v35
	ds_bpermute_b32 v34, v57, v32
	ds_bpermute_b32 v35, v57, v33
	s_waitcnt lgkmcnt(1)
	v_add_f32_e32 v32, v32, v34
	s_waitcnt lgkmcnt(0)
	v_add_f32_e32 v33, v33, v35
	ds_bpermute_b32 v34, v58, v32
	ds_bpermute_b32 v35, v58, v33
	s_waitcnt lgkmcnt(1)
	v_add_f32_e32 v32, v32, v34
	s_waitcnt lgkmcnt(0)
	v_add_f32_e32 v33, v33, v35
	ds_bpermute_b32 v34, v59, v32
	ds_bpermute_b32 v35, v59, v33
	s_waitcnt lgkmcnt(1)
	v_add_f32_e32 v32, v32, v34
	s_waitcnt lgkmcnt(0)
	v_add_f32_e32 v35, v33, v35
	ds_bpermute_b32 v34, v60, v32
	ds_bpermute_b32 v36, v60, v35
	s_waitcnt lgkmcnt(1)
	v_add_f32_e32 v32, v32, v34
	s_waitcnt lgkmcnt(0)
	v_add_f32_e32 v34, v35, v36
	ds_bpermute_b32 v33, v61, v32
	ds_bpermute_b32 v35, v61, v34
	s_and_saveexec_b64 s[12:13], vcc
	s_cbranch_execz .LBB0_140
	s_waitcnt lgkmcnt(1)
	v_add_f32_e32 v36, v32, v33
	v_lshl_add_u64 v[32:33], v[48:49], 2, s[14:15]
	global_store_dword v[32:33], v36, off
	s_and_b64 exec, exec, s[0:1]
	s_cbranch_execz .LBB0_140
	s_waitcnt lgkmcnt(0)
	v_add_f32_e32 v34, v34, v35
	v_lshl_add_u64 v[32:33], s[94:95], 2, v[32:33]
	global_store_dword v[32:33], v34, off

; __device__ __forceinline__ void prenorm_rows(const float* src0, const float* src1, int row_lo, int row_hi, const float* g, const float* scale, float* SS, bf16_t* HB) {
;     ...
;     for (int row = row_lo + gw; row < row_hi; row += 2 * NGW) {
;         const int rowb = row + NGW; const bool hasb = rowb < row_hi; const int rb = hasb ? rowb : row;
;         const float* srca = row < NTOK ? src0 + (size_t)row * D : src1 + (size_t)(row - NTOK) * D;
;         const float* srcb = rb < NTOK ? src0 + (size_t)rb * D : src1 + (size_t)(rb - NTOK) * D;
;         const int mba = row < NTOK ? (row >> 12) : 4, mbb = rb < NTOK ? (rb >> 12) : 4;
;         const f32x4* xa = (const f32x4*)srca + lane; const f32x4* xb = (const f32x4*)srcb + lane;
;         f32x4 va[4], vb[4]; float sa = 0.f, sb = 0.f;
; #pragma unroll
;         for (int j = 0; j < 4; ++j) { va[j] = xa[64 * j]; vb[j] = xb[64 * j]; }
; #pragma unroll
;         for (int j = 0; j < 4; ++j) { sa += (va[j][0] * va[j][0] + va[j][1] * va[j][1]) + (va[j][2] * va[j][2] + va[j][3] * va[j][3]); sb += (vb[j][0] * vb[j][0] + vb[j][1] * vb[j][1]) + (vb[j][2] * vb[j][2] + vb[j][3] * vb[j][3]); }
;         sa = wave_sum(sa); sb = wave_sum(sb);
;         if (lane == 0) { SS[row] = sa; if (hasb) SS[rowb] = sb; }
.Lctx_acc_loop:
	global_load_dwordx4 v[232:235], v[254:255], off nt
	global_load_dwordx4 v[236:239], v[254:255], off offset:1024 nt
	global_load_dwordx4 v[240:243], v[254:255], off offset:2048 nt
	global_load_dwordx4 v[244:247], v[254:255], off offset:3072 nt
	v_lshl_add_u64 v[254:255], v[254:255], 0, s[40:41]
	s_sub_i32 s38, s38, 1
	s_cmp_lg_u32 s38, 0
	s_waitcnt vmcnt(0)
	v_pk_add_f32 v[28:29], v[28:29], v[232:233]
	v_pk_add_f32 v[30:31], v[30:31], v[234:235]
	v_pk_add_f32 v[20:21], v[20:21], v[236:237]
	v_pk_add_f32 v[22:23], v[22:23], v[238:239]
	v_pk_add_f32 v[12:13], v[12:13], v[240:241]
	v_pk_add_f32 v[14:15], v[14:15], v[242:243]
	v_pk_add_f32 v[4:5], v[4:5], v[244:245]
	v_pk_add_f32 v[6:7], v[6:7], v[246:247]
	s_cbranch_scc1 .Lctx_acc_loop
	v_mul_f32_e32 v32, v29, v29
	v_mul_f32_e32 v33, v31, v31
	s_waitcnt vmcnt(6)
	v_mul_f32_e32 v34, v21, v21
	v_mul_f32_e32 v35, v23, v23
	s_waitcnt vmcnt(5)
	v_mul_f32_e32 v36, v13, v13
	v_mul_f32_e32 v37, v15, v15
	v_fmac_f32_e32 v32, v28, v28
	v_fmac_f32_e32 v33, v30, v30
	v_fmac_f32_e32 v34, v20, v20
	v_fmac_f32_e32 v35, v22, v22
	s_waitcnt vmcnt(4)
	v_mul_f32_e32 v38, v5, v5
	v_mul_f32_e32 v39, v7, v7
	v_fmac_f32_e32 v36, v12, v12
	v_fmac_f32_e32 v37, v14, v14
	v_add_f32_e32 v32, v32, v33
	v_add_f32_e32 v34, v34, v35
	v_fmac_f32_e32 v38, v4, v4
	v_fmac_f32_e32 v39, v6, v6
	v_add_f32_e32 v36, v36, v37
	v_add_f32_e32 v38, v38, v39
	v_add_f32_e32 v32, v32, v34
	v_add_f32_e32 v32, v32, v36
	v_add_f32_e32 v32, v32, v38
	s_waitcnt vmcnt(3)
	v_mul_f32_e32 v33, v25, v25
	v_mul_f32_e32 v50, v27, v27
	s_waitcnt vmcnt(2)
	v_mul_f32_e32 v35, v17, v17
	v_mul_f32_e32 v51, v19, v19
	s_waitcnt vmcnt(1)
	v_mul_f32_e32 v37, v9, v9
	v_mul_f32_e32 v52, v11, v11
	v_fmac_f32_e32 v33, v24, v24
	v_fmac_f32_e32 v50, v26, v26
	v_fmac_f32_e32 v35, v16, v16
	v_fmac_f32_e32 v51, v18, v18
	s_waitcnt vmcnt(0)
	v_mul_f32_e32 v39, v1, v1
	v_mul_f32_e32 v53, v3, v3
	v_fmac_f32_e32 v37, v8, v8
	v_fmac_f32_e32 v52, v10, v10
	v_add_f32_e32 v33, v33, v50
	v_add_f32_e32 v34, v35, v51
	v_fmac_f32_e32 v39, v0, v0
	v_fmac_f32_e32 v53, v2, v2
	v_add_f32_e32 v35, v37, v52
	v_add_f32_e32 v33, v33, v34
	v_add_f32_e32 v36, v39, v53
	v_add_f32_e32 v33, v33, v35
	v_add_f32_e32 v33, v33, v36
	ds_bpermute_b32 v34, v54, v32
	ds_bpermute_b32 v35, v54, v33
	s_waitcnt lgkmcnt(1)
	v_add_f32_e32 v32, v32, v34
	s_waitcnt lgkmcnt(0)
	v_add_f32_e32 v33, v33, v35
	ds_bpermute_b32 v34, v55, v32
	ds_bpermute_b32 v35, v55, v33
	s_waitcnt lgkmcnt(1)
	v_add_f32_e32 v32, v32, v34
	s_waitcnt lgkmcnt(0)
	v_add_f32_e32 v33, v33, v35
	ds_bpermute_b32 v34, v56, v32
	ds_bpermute_b32 v35, v56, v33
	s_waitcnt lgkmcnt(1)
	v_add_f32_e32 v32, v32, v34
	s_waitcnt lgkmcnt(0)
	v_add_f32_e32 v33, v33, v35
	ds_bpermute_b32 v34, v57, v32
	ds_bpermute_b32 v35, v57, v33
	s_waitcnt lgkmcnt(1)
	v_add_f32_e32 v32, v32, v34
	s_waitcnt lgkmcnt(0)
	v_add_f32_e32 v35, v33, v35
	ds_bpermute_b32 v34, v58, v32
	ds_bpermute_b32 v36, v58, v35
	s_waitcnt lgkmcnt(1)
	v_add_f32_e32 v32, v32, v34
	s_waitcnt lgkmcnt(0)
	v_add_f32_e32 v34, v35, v36
	ds_bpermute_b32 v33, v59, v32
	ds_bpermute_b32 v35, v59, v34
	s_and_saveexec_b64 s[2:3], vcc
	s_cbranch_execz .LBB0_408
	s_waitcnt lgkmcnt(1)
	v_add_f32_e32 v36, v32, v33
	v_lshl_add_u64 v[32:33], v[46:47], 2, s[14:15]
	global_store_dword v[32:33], v36, off
	s_and_b64 exec, exec, s[0:1]
	s_cbranch_execz .LBB0_408
	s_waitcnt lgkmcnt(0)
	v_add_f32_e32 v34, v34, v35
	v_lshl_add_u64 v[32:33], s[94:95], 2, v[32:33]
	global_store_dword v[32:33], v34, off
